# weight copies stored write-through (sc0 sc1); post-down L0-2 and post-W_o L0 barriers skip buffer_wbl2 in local mode
# baseline (speedup 1.0000x reference)
.LBB0_763:
	v_or_b32_e32 v73, s2, v69
	v_readlane_b32 s2, v250, 40
	v_lshlrev_b32_e32 v0, 1, v66
	v_readlane_b32 s3, v250, 41
	s_waitcnt vmcnt(0)
	v_cvt_pk_bf16_f32 v74, v2, v6
	v_cvt_pk_bf16_f32 v75, v10, v14
	v_lshl_add_u64 v[66:67], s[2:3], 0, v[0:1]
	v_lshlrev_b32_e32 v0, 11, v73
	v_cvt_pk_bf16_f32 v76, v18, v22
	v_cvt_pk_bf16_f32 v77, v26, v30
	v_lshl_add_u64 v[66:67], v[66:67], 0, v[0:1]
	s_movk_i32 s0, 0x1000
	v_cvt_pk_bf16_f32 v78, v34, v38
	v_cvt_pk_bf16_f32 v79, v42, v46
	v_cvt_pk_bf16_f32 v80, v50, v54
	v_cvt_pk_bf16_f32 v81, v58, v62
	global_store_dwordx4 v[66:67], v[74:77], off sc0 sc1
	global_store_dwordx4 v[66:67], v[78:81], off offset:16 sc0 sc1
	v_add_co_u32_e32 v10, vcc, s0, v66
	v_cvt_pk_bf16_f32 v74, v3, v7
	v_cvt_pk_bf16_f32 v75, v11, v15
	v_cvt_pk_bf16_f32 v76, v19, v23
	v_cvt_pk_bf16_f32 v77, v27, v31
	v_cvt_pk_bf16_f32 v78, v35, v39
	v_cvt_pk_bf16_f32 v79, v43, v47
	v_cvt_pk_bf16_f32 v80, v51, v55
	v_cvt_pk_bf16_f32 v81, v59, v63
	global_store_dwordx4 v[66:67], v[74:77], off offset:2048 sc0 sc1
	global_store_dwordx4 v[66:67], v[78:81], off offset:2064 sc0 sc1
	v_addc_co_u32_e32 v11, vcc, 0, v67, vcc
	v_cvt_pk_bf16_f32 v74, v4, v8
	v_cvt_pk_bf16_f32 v75, v12, v16
	v_cvt_pk_bf16_f32 v76, v20, v24
	v_cvt_pk_bf16_f32 v77, v28, v32
	v_cvt_pk_bf16_f32 v2, v5, v9
	v_cvt_pk_bf16_f32 v3, v13, v17
	v_cvt_pk_bf16_f32 v4, v21, v25
	v_cvt_pk_bf16_f32 v5, v29, v33
	v_cvt_pk_bf16_f32 v78, v36, v40
	v_cvt_pk_bf16_f32 v79, v44, v48
	v_cvt_pk_bf16_f32 v80, v52, v56
	v_cvt_pk_bf16_f32 v81, v60, v64
	global_store_dwordx4 v[10:11], v[74:77], off sc0 sc1
	global_store_dwordx4 v[10:11], v[78:81], off offset:16 sc0 sc1
	v_cvt_pk_bf16_f32 v6, v37, v41
	v_cvt_pk_bf16_f32 v7, v45, v49
	v_cvt_pk_bf16_f32 v8, v53, v57
	v_cvt_pk_bf16_f32 v9, v61, v65
	global_store_dwordx4 v[10:11], v[2:5], off offset:2048 sc0 sc1
	global_store_dwordx4 v[10:11], v[6:9], off offset:2064 sc0 sc1

.LBB0_765:
	s_cmpk_lt_i32 s6, 0x280
	s_mov_b64 s[2:3], -1
	s_cbranch_scc0 .LBB0_776
	s_cmpk_gt_i32 s6, 0x17f
	s_cbranch_scc0 .LBB0_768
	s_and_b32 s0, s7, 0x3c0
	v_or_b32_e32 v73, s0, v69
	s_and_b32 s0, s9, 0x7fffffc0
	v_readlane_b32 s72, v251, 34
	v_add_u32_e32 v66, s0, v71
	v_lshlrev_b32_e32 v0, 2, v73
	v_readlane_b32 s84, v251, 46
	v_readlane_b32 s85, v251, 47
	v_mov_b32_e32 v67, v1
	v_lshlrev_b64 v[2:3], 12, v[66:67]
	v_lshl_add_u64 v[62:63], s[84:85], 0, v[0:1]
	v_or_b32_e32 v0, 1, v66
	v_lshlrev_b64 v[6:7], 12, v[0:1]
	v_or_b32_e32 v0, 2, v66
	v_lshlrev_b64 v[10:11], 12, v[0:1]
	v_or_b32_e32 v0, 3, v66
	v_lshlrev_b64 v[14:15], 12, v[0:1]
	v_or_b32_e32 v0, 4, v66
	v_lshlrev_b64 v[18:19], 12, v[0:1]
	v_or_b32_e32 v0, 5, v66
	v_lshlrev_b64 v[22:23], 12, v[0:1]
	v_or_b32_e32 v0, 6, v66
	v_lshlrev_b64 v[26:27], 12, v[0:1]
	v_or_b32_e32 v0, 7, v66
	v_lshlrev_b64 v[30:31], 12, v[0:1]
	v_or_b32_e32 v0, 8, v66
	v_lshlrev_b64 v[34:35], 12, v[0:1]
	v_or_b32_e32 v0, 9, v66
	v_lshlrev_b64 v[38:39], 12, v[0:1]
	v_or_b32_e32 v0, 10, v66
	v_lshlrev_b64 v[42:43], 12, v[0:1]
	v_or_b32_e32 v0, 11, v66
	v_lshlrev_b64 v[46:47], 12, v[0:1]
	v_or_b32_e32 v0, 12, v66
	v_lshlrev_b64 v[50:51], 12, v[0:1]
	v_or_b32_e32 v0, 13, v66
	v_lshlrev_b64 v[54:55], 12, v[0:1]
	v_or_b32_e32 v0, 14, v66
	v_lshlrev_b64 v[58:59], 12, v[0:1]
	v_or_b32_e32 v0, 15, v66
	v_lshl_add_u64 v[2:3], v[62:63], 0, v[2:3]
	v_lshl_add_u64 v[6:7], v[62:63], 0, v[6:7]
	v_lshl_add_u64 v[10:11], v[62:63], 0, v[10:11]
	v_lshl_add_u64 v[14:15], v[62:63], 0, v[14:15]
	v_lshl_add_u64 v[18:19], v[62:63], 0, v[18:19]
	v_lshl_add_u64 v[22:23], v[62:63], 0, v[22:23]
	v_lshl_add_u64 v[26:27], v[62:63], 0, v[26:27]
	v_lshl_add_u64 v[30:31], v[62:63], 0, v[30:31]
	v_lshlrev_b64 v[64:65], 12, v[0:1]
	global_load_dwordx4 v[2:5], v[2:3], off
	v_lshl_add_u64 v[34:35], v[62:63], 0, v[34:35]
	global_load_dwordx4 v[6:9], v[6:7], off
	v_lshl_add_u64 v[38:39], v[62:63], 0, v[38:39]
	global_load_dwordx4 v[10:13], v[10:11], off
	v_lshl_add_u64 v[42:43], v[62:63], 0, v[42:43]
	global_load_dwordx4 v[14:17], v[14:15], off
	v_lshl_add_u64 v[46:47], v[62:63], 0, v[46:47]
	global_load_dwordx4 v[18:21], v[18:19], off
	v_lshl_add_u64 v[50:51], v[62:63], 0, v[50:51]
	global_load_dwordx4 v[22:25], v[22:23], off
	v_lshl_add_u64 v[54:55], v[62:63], 0, v[54:55]
	global_load_dwordx4 v[26:29], v[26:27], off
	v_lshl_add_u64 v[58:59], v[62:63], 0, v[58:59]
	global_load_dwordx4 v[30:33], v[30:31], off
	v_lshl_add_u64 v[62:63], v[62:63], 0, v[64:65]
	global_load_dwordx4 v[34:37], v[34:35], off
	v_readlane_b32 s2, v251, 28
	global_load_dwordx4 v[38:41], v[38:39], off
	v_readlane_b32 s3, v251, 29
	global_load_dwordx4 v[42:45], v[42:43], off
	v_lshlrev_b32_e32 v0, 11, v73
	global_load_dwordx4 v[46:49], v[46:47], off
	v_lshl_add_u64 v[66:67], v[66:67], 1, s[2:3]
	global_load_dwordx4 v[50:53], v[50:51], off
	v_lshl_add_u64 v[66:67], v[66:67], 0, v[0:1]
	global_load_dwordx4 v[54:57], v[54:55], off
	s_movk_i32 s0, 0x1000
	global_load_dwordx4 v[58:61], v[58:59], off
	v_readlane_b32 s73, v251, 35
	global_load_dwordx4 v[62:65], v[62:63], off
	v_readlane_b32 s74, v251, 36
	v_readlane_b32 s75, v251, 37
	v_readlane_b32 s76, v251, 38
	v_readlane_b32 s77, v251, 39
	v_readlane_b32 s78, v251, 40
	v_readlane_b32 s79, v251, 41
	v_readlane_b32 s80, v251, 42
	v_readlane_b32 s81, v251, 43
	v_readlane_b32 s82, v251, 44
	v_readlane_b32 s83, v251, 45
	v_readlane_b32 s86, v251, 48
	v_readlane_b32 s87, v251, 49
	s_mov_b64 s[2:3], 0
	s_waitcnt vmcnt(0)
	v_cvt_pk_bf16_f32 v74, v2, v6
	v_cvt_pk_bf16_f32 v2, v5, v9
	v_cvt_pk_bf16_f32 v75, v10, v14
	v_add_co_u32_e32 v10, vcc, s0, v66
	v_cvt_pk_bf16_f32 v76, v18, v22
	v_cvt_pk_bf16_f32 v77, v26, v30
	v_cvt_pk_bf16_f32 v5, v29, v33
	v_cvt_pk_bf16_f32 v78, v34, v38
	v_cvt_pk_bf16_f32 v6, v37, v41
	v_cvt_pk_bf16_f32 v79, v42, v46
	v_cvt_pk_bf16_f32 v80, v50, v54
	v_cvt_pk_bf16_f32 v81, v58, v62
	global_store_dwordx4 v[66:67], v[74:77], off sc0 sc1
	global_store_dwordx4 v[66:67], v[78:81], off offset:16 sc0 sc1
	v_cvt_pk_bf16_f32 v9, v61, v65
	v_cvt_pk_bf16_f32 v74, v3, v7
	v_cvt_pk_bf16_f32 v75, v11, v15
	v_cvt_pk_bf16_f32 v76, v19, v23
	v_cvt_pk_bf16_f32 v77, v27, v31
	v_cvt_pk_bf16_f32 v78, v35, v39
	v_cvt_pk_bf16_f32 v79, v43, v47
	v_cvt_pk_bf16_f32 v80, v51, v55
	v_cvt_pk_bf16_f32 v81, v59, v63
	global_store_dwordx4 v[66:67], v[74:77], off offset:2048 sc0 sc1
	global_store_dwordx4 v[66:67], v[78:81], off offset:2064 sc0 sc1
	v_addc_co_u32_e32 v11, vcc, 0, v67, vcc
	v_cvt_pk_bf16_f32 v74, v4, v8
	v_cvt_pk_bf16_f32 v75, v12, v16
	v_cvt_pk_bf16_f32 v76, v20, v24
	v_cvt_pk_bf16_f32 v77, v28, v32
	v_cvt_pk_bf16_f32 v3, v13, v17
	v_cvt_pk_bf16_f32 v4, v21, v25
	v_cvt_pk_bf16_f32 v78, v36, v40
	v_cvt_pk_bf16_f32 v79, v44, v48
	v_cvt_pk_bf16_f32 v80, v52, v56
	v_cvt_pk_bf16_f32 v81, v60, v64
	global_store_dwordx4 v[10:11], v[74:77], off sc0 sc1
	global_store_dwordx4 v[10:11], v[78:81], off offset:16 sc0 sc1
	v_cvt_pk_bf16_f32 v7, v45, v49
	v_cvt_pk_bf16_f32 v8, v53, v57
	global_store_dwordx4 v[10:11], v[2:5], off offset:2048 sc0 sc1
	global_store_dwordx4 v[10:11], v[6:9], off offset:2064 sc0 sc1

.LBB0_774:
	v_readlane_b32 s2, v251, 30
	v_readlane_b32 s3, v251, 31
	v_ashrrev_i32_e32 v83, 31, v0
	v_mov_b32_e32 v82, v0
	v_lshl_add_u64 v[66:67], v[66:67], 1, s[2:3]
	v_lshlrev_b64 v[82:83], 11, v[82:83]
	s_waitcnt vmcnt(0)
	v_cvt_pk_bf16_f32 v74, v62, v54
	v_cvt_pk_bf16_f32 v75, v58, v46
	v_cvt_pk_bf16_f32 v76, v50, v38
	v_cvt_pk_bf16_f32 v77, v42, v34
	v_cvt_pk_bf16_f32 v81, v14, v2
	v_lshl_add_u64 v[82:83], v[66:67], 0, v[82:83]
	v_add_u32_e32 v2, 1, v0
	v_cvt_pk_bf16_f32 v78, v30, v22
	v_cvt_pk_bf16_f32 v79, v26, v10
	v_cvt_pk_bf16_f32 v80, v18, v6
	global_store_dwordx4 v[82:83], v[74:77], off sc0 sc1
	global_store_dwordx4 v[82:83], v[78:81], off offset:16 sc0 sc1
	v_add_u32_e32 v6, 3, v0
	v_cvt_pk_bf16_f32 v74, v63, v55
	v_cvt_pk_bf16_f32 v81, v15, v3
	v_ashrrev_i32_e32 v3, 31, v2
	v_lshlrev_b64 v[2:3], 11, v[2:3]
	v_cvt_pk_bf16_f32 v75, v59, v47
	v_cvt_pk_bf16_f32 v76, v51, v39
	v_cvt_pk_bf16_f32 v77, v43, v35
	v_lshl_add_u64 v[2:3], v[66:67], 0, v[2:3]
	v_cvt_pk_bf16_f32 v78, v31, v23
	v_cvt_pk_bf16_f32 v79, v27, v11
	v_cvt_pk_bf16_f32 v80, v19, v7
	global_store_dwordx4 v[2:3], v[74:77], off sc0 sc1
	global_store_dwordx4 v[2:3], v[78:81], off offset:16 sc0 sc1
	v_add_u32_e32 v2, 2, v0
	v_ashrrev_i32_e32 v3, 31, v2
	v_ashrrev_i32_e32 v7, 31, v6
	v_lshlrev_b64 v[2:3], 11, v[2:3]
	v_lshlrev_b64 v[6:7], 11, v[6:7]
	v_cvt_pk_bf16_f32 v74, v64, v56
	v_cvt_pk_bf16_f32 v75, v60, v48
	v_cvt_pk_bf16_f32 v76, v52, v40
	v_cvt_pk_bf16_f32 v77, v44, v36
	v_lshl_add_u64 v[2:3], v[66:67], 0, v[2:3]
	v_cvt_pk_bf16_f32 v34, v65, v57
	v_cvt_pk_bf16_f32 v35, v61, v49
	v_cvt_pk_bf16_f32 v36, v53, v41
	v_cvt_pk_bf16_f32 v37, v45, v37
	v_lshl_add_u64 v[6:7], v[66:67], 0, v[6:7]
	v_cvt_pk_bf16_f32 v78, v32, v24
	v_cvt_pk_bf16_f32 v79, v28, v12
	v_cvt_pk_bf16_f32 v80, v20, v8
	v_cvt_pk_bf16_f32 v81, v16, v4
	global_store_dwordx4 v[2:3], v[74:77], off sc0 sc1
	global_store_dwordx4 v[2:3], v[78:81], off offset:16 sc0 sc1
	v_cvt_pk_bf16_f32 v2, v33, v25
	v_cvt_pk_bf16_f32 v3, v29, v13
	v_cvt_pk_bf16_f32 v4, v21, v9
	v_cvt_pk_bf16_f32 v5, v17, v5
	global_store_dwordx4 v[6:7], v[34:37], off sc0 sc1
	global_store_dwordx4 v[6:7], v[2:5], off offset:16 sc0 sc1

.LBB0_776:
	s_andn2_b64 vcc, exec, s[2:3]
	s_cbranch_vccnz .LBB0_764
	s_cmpk_gt_u32 s6, 0x7ff
	s_mov_b64 s[2:3], -1
	s_cbranch_scc0 .LBB0_779
	s_and_b32 s0, s7, 0x3c0
	v_or_b32_e32 v73, s0, v69
	s_and_b32 s0, s9, 0x7fffffc0
	v_readlane_b32 s72, v251, 4
	v_add_u32_e32 v66, s0, v72
	v_lshlrev_b32_e32 v0, 2, v73
	v_readlane_b32 s84, v251, 16
	v_readlane_b32 s85, v251, 17
	v_mov_b32_e32 v67, v1
	v_lshlrev_b64 v[2:3], 12, v[66:67]
	v_lshl_add_u64 v[62:63], s[84:85], 0, v[0:1]
	v_or_b32_e32 v0, 1, v66
	v_lshlrev_b64 v[6:7], 12, v[0:1]
	v_or_b32_e32 v0, 2, v66
	v_lshlrev_b64 v[10:11], 12, v[0:1]
	v_or_b32_e32 v0, 3, v66
	v_lshlrev_b64 v[14:15], 12, v[0:1]
	v_or_b32_e32 v0, 4, v66
	v_lshlrev_b64 v[18:19], 12, v[0:1]
	v_or_b32_e32 v0, 5, v66
	v_lshlrev_b64 v[22:23], 12, v[0:1]
	v_or_b32_e32 v0, 6, v66
	v_lshlrev_b64 v[26:27], 12, v[0:1]
	v_or_b32_e32 v0, 7, v66
	v_lshlrev_b64 v[30:31], 12, v[0:1]
	v_or_b32_e32 v0, 8, v66
	v_lshlrev_b64 v[34:35], 12, v[0:1]
	v_or_b32_e32 v0, 9, v66
	v_lshlrev_b64 v[38:39], 12, v[0:1]
	v_or_b32_e32 v0, 10, v66
	v_lshlrev_b64 v[42:43], 12, v[0:1]
	v_or_b32_e32 v0, 11, v66
	v_lshlrev_b64 v[46:47], 12, v[0:1]
	v_or_b32_e32 v0, 12, v66
	v_lshlrev_b64 v[50:51], 12, v[0:1]
	v_or_b32_e32 v0, 13, v66
	v_lshlrev_b64 v[54:55], 12, v[0:1]
	v_or_b32_e32 v0, 14, v66
	v_lshlrev_b64 v[58:59], 12, v[0:1]
	v_or_b32_e32 v0, 15, v66
	v_lshl_add_u64 v[2:3], v[62:63], 0, v[2:3]
	v_lshl_add_u64 v[6:7], v[62:63], 0, v[6:7]
	v_lshl_add_u64 v[10:11], v[62:63], 0, v[10:11]
	v_lshl_add_u64 v[14:15], v[62:63], 0, v[14:15]
	v_lshl_add_u64 v[18:19], v[62:63], 0, v[18:19]
	v_lshl_add_u64 v[22:23], v[62:63], 0, v[22:23]
	v_lshl_add_u64 v[26:27], v[62:63], 0, v[26:27]
	v_lshl_add_u64 v[30:31], v[62:63], 0, v[30:31]
	v_lshlrev_b64 v[64:65], 12, v[0:1]
	global_load_dwordx4 v[2:5], v[2:3], off
	v_lshl_add_u64 v[34:35], v[62:63], 0, v[34:35]
	global_load_dwordx4 v[6:9], v[6:7], off
	v_lshl_add_u64 v[38:39], v[62:63], 0, v[38:39]
	global_load_dwordx4 v[10:13], v[10:11], off
	v_lshl_add_u64 v[42:43], v[62:63], 0, v[42:43]
	global_load_dwordx4 v[14:17], v[14:15], off
	v_lshl_add_u64 v[46:47], v[62:63], 0, v[46:47]
	global_load_dwordx4 v[18:21], v[18:19], off
	v_lshl_add_u64 v[50:51], v[62:63], 0, v[50:51]
	global_load_dwordx4 v[22:25], v[22:23], off
	v_lshl_add_u64 v[54:55], v[62:63], 0, v[54:55]
	global_load_dwordx4 v[26:29], v[26:27], off
	v_lshl_add_u64 v[58:59], v[62:63], 0, v[58:59]
	global_load_dwordx4 v[30:33], v[30:31], off
	v_lshl_add_u64 v[62:63], v[62:63], 0, v[64:65]
	global_load_dwordx4 v[34:37], v[34:35], off
	v_readlane_b32 s2, v250, 38
	global_load_dwordx4 v[38:41], v[38:39], off
	v_readlane_b32 s3, v250, 39
	global_load_dwordx4 v[42:45], v[42:43], off
	v_mul_u32_u24_e32 v0, 0xb00, v73
	global_load_dwordx4 v[46:49], v[46:47], off
	v_lshl_add_u64 v[66:67], v[66:67], 1, s[2:3]
	global_load_dwordx4 v[50:53], v[50:51], off
	v_lshlrev_b32_e32 v0, 1, v0
	global_load_dwordx4 v[54:57], v[54:55], off
	v_lshl_add_u64 v[66:67], v[66:67], 0, v[0:1]
	global_load_dwordx4 v[58:61], v[58:59], off
	s_movk_i32 s0, 0x1000
	global_load_dwordx4 v[62:65], v[62:63], off
	v_readlane_b32 s73, v251, 5
	v_readlane_b32 s74, v251, 6
	v_readlane_b32 s75, v251, 7
	v_readlane_b32 s76, v251, 8
	v_readlane_b32 s77, v251, 9
	v_readlane_b32 s78, v251, 10
	v_readlane_b32 s79, v251, 11
	v_readlane_b32 s80, v251, 12
	v_readlane_b32 s81, v251, 13
	v_readlane_b32 s82, v251, 14
	v_readlane_b32 s83, v251, 15
	v_readlane_b32 s86, v251, 18
	v_readlane_b32 s87, v251, 19
	s_mov_b64 s[2:3], 0
	s_waitcnt vmcnt(0)
	v_cvt_pk_bf16_f32 v74, v2, v6
	v_add_co_u32_e32 v2, vcc, s0, v66
	s_movk_i32 s0, 0x2000
	v_cvt_pk_bf16_f32 v75, v10, v14
	v_cvt_pk_bf16_f32 v76, v18, v22
	v_cvt_pk_bf16_f32 v77, v26, v30
	v_cvt_pk_bf16_f32 v78, v34, v38
	v_cvt_pk_bf16_f32 v6, v37, v41
	v_cvt_pk_bf16_f32 v79, v42, v46
	v_cvt_pk_bf16_f32 v80, v50, v54
	v_cvt_pk_bf16_f32 v81, v58, v62
	global_store_dwordx4 v[66:67], v[74:77], off sc0 sc1
	global_store_dwordx4 v[66:67], v[78:81], off offset:16 sc0 sc1
	s_nop 0
	v_cvt_pk_bf16_f32 v74, v3, v7
	v_cvt_pk_bf16_f32 v75, v11, v15
	v_cvt_pk_bf16_f32 v76, v19, v23
	v_cvt_pk_bf16_f32 v77, v27, v31
	v_addc_co_u32_e32 v3, vcc, 0, v67, vcc
	v_cvt_pk_bf16_f32 v78, v35, v39
	v_cvt_pk_bf16_f32 v79, v43, v47
	v_cvt_pk_bf16_f32 v80, v51, v55
	v_cvt_pk_bf16_f32 v81, v59, v63
	global_store_dwordx4 v[2:3], v[74:77], off offset:1536 sc0 sc1
	global_store_dwordx4 v[2:3], v[78:81], off offset:1552 sc0 sc1
	v_add_co_u32_e32 v2, vcc, s0, v66
	v_cvt_pk_bf16_f32 v74, v4, v8
	s_nop 0
	v_addc_co_u32_e32 v3, vcc, 0, v67, vcc
	v_cvt_pk_bf16_f32 v75, v12, v16
	v_cvt_pk_bf16_f32 v76, v20, v24
	v_cvt_pk_bf16_f32 v77, v28, v32
	v_add_co_u32_e32 v10, vcc, 0x4000, v66
	v_cvt_pk_bf16_f32 v78, v36, v40
	v_cvt_pk_bf16_f32 v79, v44, v48
	v_cvt_pk_bf16_f32 v80, v52, v56
	v_cvt_pk_bf16_f32 v81, v60, v64
	global_store_dwordx4 v[2:3], v[74:77], off offset:3072 sc0 sc1
	global_store_dwordx4 v[2:3], v[78:81], off offset:3088 sc0 sc1
	v_cvt_pk_bf16_f32 v2, v5, v9
	v_cvt_pk_bf16_f32 v3, v13, v17
	v_cvt_pk_bf16_f32 v4, v21, v25
	v_cvt_pk_bf16_f32 v5, v29, v33
	v_addc_co_u32_e32 v11, vcc, 0, v67, vcc
	v_cvt_pk_bf16_f32 v7, v45, v49
	v_cvt_pk_bf16_f32 v8, v53, v57
	v_cvt_pk_bf16_f32 v9, v61, v65
	global_store_dwordx4 v[10:11], v[2:5], off offset:512 sc0 sc1
	global_store_dwordx4 v[10:11], v[6:9], off offset:528 sc0 sc1

.LBB0_786:
	v_or_b32_e32 v80, s2, v69
	v_readlane_b32 s2, v250, 40
	v_lshlrev_b32_e32 v0, 1, v66
	v_readlane_b32 s3, v250, 41
	s_waitcnt vmcnt(0)
	v_cvt_pk_bf16_f32 v72, v2, v6
	v_cvt_pk_bf16_f32 v73, v10, v14
	v_lshl_add_u64 v[66:67], s[2:3], 0, v[0:1]
	v_lshlrev_b32_e32 v0, 11, v80
	v_cvt_pk_bf16_f32 v74, v18, v22
	v_cvt_pk_bf16_f32 v75, v26, v30
	v_lshl_add_u64 v[66:67], v[66:67], 0, v[0:1]
	s_movk_i32 s0, 0x1000
	v_cvt_pk_bf16_f32 v76, v34, v38
	v_cvt_pk_bf16_f32 v77, v42, v46
	v_cvt_pk_bf16_f32 v78, v50, v54
	v_cvt_pk_bf16_f32 v79, v58, v62
	global_store_dwordx4 v[66:67], v[72:75], off sc0 sc1
	global_store_dwordx4 v[66:67], v[76:79], off offset:16 sc0 sc1
	v_add_co_u32_e32 v10, vcc, s0, v66
	v_cvt_pk_bf16_f32 v72, v3, v7
	v_cvt_pk_bf16_f32 v73, v11, v15
	v_cvt_pk_bf16_f32 v74, v19, v23
	v_cvt_pk_bf16_f32 v75, v27, v31
	v_cvt_pk_bf16_f32 v76, v35, v39
	v_cvt_pk_bf16_f32 v77, v43, v47
	v_cvt_pk_bf16_f32 v78, v51, v55
	v_cvt_pk_bf16_f32 v79, v59, v63
	global_store_dwordx4 v[66:67], v[72:75], off offset:2048 sc0 sc1
	global_store_dwordx4 v[66:67], v[76:79], off offset:2064 sc0 sc1
	v_addc_co_u32_e32 v11, vcc, 0, v67, vcc
	v_cvt_pk_bf16_f32 v72, v4, v8
	v_cvt_pk_bf16_f32 v73, v12, v16
	v_cvt_pk_bf16_f32 v74, v20, v24
	v_cvt_pk_bf16_f32 v75, v28, v32
	v_cvt_pk_bf16_f32 v2, v5, v9
	v_cvt_pk_bf16_f32 v3, v13, v17
	v_cvt_pk_bf16_f32 v4, v21, v25
	v_cvt_pk_bf16_f32 v5, v29, v33
	v_cvt_pk_bf16_f32 v76, v36, v40
	v_cvt_pk_bf16_f32 v77, v44, v48
	v_cvt_pk_bf16_f32 v78, v52, v56
	v_cvt_pk_bf16_f32 v79, v60, v64
	global_store_dwordx4 v[10:11], v[72:75], off sc0 sc1
	global_store_dwordx4 v[10:11], v[76:79], off offset:16 sc0 sc1
	v_cvt_pk_bf16_f32 v6, v37, v41
	v_cvt_pk_bf16_f32 v7, v45, v49
	v_cvt_pk_bf16_f32 v8, v53, v57
	v_cvt_pk_bf16_f32 v9, v61, v65
	global_store_dwordx4 v[10:11], v[2:5], off offset:2048 sc0 sc1
	global_store_dwordx4 v[10:11], v[6:9], off offset:2064 sc0 sc1

.LBB0_788:
	s_cmpk_lt_i32 s4, 0x280
	s_mov_b64 s[2:3], -1
	s_cbranch_scc0 .LBB0_799
	s_cmpk_gt_i32 s4, 0x17f
	s_cbranch_scc0 .LBB0_791
	s_and_b32 s0, s6, 0x3c0
	v_or_b32_e32 v80, s0, v69
	s_and_b32 s0, s8, 0x7fffffc0
	v_readlane_b32 s72, v251, 34
	v_add_u32_e32 v66, s0, v70
	v_lshlrev_b32_e32 v0, 2, v80
	v_readlane_b32 s84, v251, 46
	v_readlane_b32 s85, v251, 47
	v_mov_b32_e32 v67, v1
	v_lshlrev_b64 v[2:3], 12, v[66:67]
	v_lshl_add_u64 v[62:63], s[84:85], 0, v[0:1]
	v_or_b32_e32 v0, 1, v66
	v_lshlrev_b64 v[6:7], 12, v[0:1]
	v_or_b32_e32 v0, 2, v66
	v_lshlrev_b64 v[10:11], 12, v[0:1]
	v_or_b32_e32 v0, 3, v66
	v_lshlrev_b64 v[14:15], 12, v[0:1]
	v_or_b32_e32 v0, 4, v66
	v_lshlrev_b64 v[18:19], 12, v[0:1]
	v_or_b32_e32 v0, 5, v66
	v_lshlrev_b64 v[22:23], 12, v[0:1]
	v_or_b32_e32 v0, 6, v66
	v_lshlrev_b64 v[26:27], 12, v[0:1]
	v_or_b32_e32 v0, 7, v66
	v_lshlrev_b64 v[30:31], 12, v[0:1]
	v_or_b32_e32 v0, 8, v66
	v_lshlrev_b64 v[34:35], 12, v[0:1]
	v_or_b32_e32 v0, 9, v66
	v_lshlrev_b64 v[38:39], 12, v[0:1]
	v_or_b32_e32 v0, 10, v66
	v_lshlrev_b64 v[42:43], 12, v[0:1]
	v_or_b32_e32 v0, 11, v66
	v_lshlrev_b64 v[46:47], 12, v[0:1]
	v_or_b32_e32 v0, 12, v66
	v_lshlrev_b64 v[50:51], 12, v[0:1]
	v_or_b32_e32 v0, 13, v66
	v_lshlrev_b64 v[54:55], 12, v[0:1]
	v_or_b32_e32 v0, 14, v66
	v_lshlrev_b64 v[58:59], 12, v[0:1]
	v_or_b32_e32 v0, 15, v66
	v_lshl_add_u64 v[2:3], v[62:63], 0, v[2:3]
	v_lshl_add_u64 v[6:7], v[62:63], 0, v[6:7]
	v_lshl_add_u64 v[10:11], v[62:63], 0, v[10:11]
	v_lshl_add_u64 v[14:15], v[62:63], 0, v[14:15]
	v_lshl_add_u64 v[18:19], v[62:63], 0, v[18:19]
	v_lshl_add_u64 v[22:23], v[62:63], 0, v[22:23]
	v_lshl_add_u64 v[26:27], v[62:63], 0, v[26:27]
	v_lshl_add_u64 v[30:31], v[62:63], 0, v[30:31]
	v_lshlrev_b64 v[64:65], 12, v[0:1]
	global_load_dwordx4 v[2:5], v[2:3], off
	v_lshl_add_u64 v[34:35], v[62:63], 0, v[34:35]
	global_load_dwordx4 v[6:9], v[6:7], off
	v_lshl_add_u64 v[38:39], v[62:63], 0, v[38:39]
	global_load_dwordx4 v[10:13], v[10:11], off
	v_lshl_add_u64 v[42:43], v[62:63], 0, v[42:43]
	global_load_dwordx4 v[14:17], v[14:15], off
	v_lshl_add_u64 v[46:47], v[62:63], 0, v[46:47]
	global_load_dwordx4 v[18:21], v[18:19], off
	v_lshl_add_u64 v[50:51], v[62:63], 0, v[50:51]
	global_load_dwordx4 v[22:25], v[22:23], off
	v_lshl_add_u64 v[54:55], v[62:63], 0, v[54:55]
	global_load_dwordx4 v[26:29], v[26:27], off
	v_lshl_add_u64 v[58:59], v[62:63], 0, v[58:59]
	global_load_dwordx4 v[30:33], v[30:31], off
	v_lshl_add_u64 v[62:63], v[62:63], 0, v[64:65]
	global_load_dwordx4 v[34:37], v[34:35], off
	v_readlane_b32 s2, v251, 28
	global_load_dwordx4 v[38:41], v[38:39], off
	v_readlane_b32 s3, v251, 29
	global_load_dwordx4 v[42:45], v[42:43], off
	v_lshlrev_b32_e32 v0, 11, v80
	global_load_dwordx4 v[46:49], v[46:47], off
	v_lshl_add_u64 v[66:67], v[66:67], 1, s[2:3]
	global_load_dwordx4 v[50:53], v[50:51], off
	v_lshl_add_u64 v[66:67], v[66:67], 0, v[0:1]
	global_load_dwordx4 v[54:57], v[54:55], off
	s_movk_i32 s0, 0x1000
	global_load_dwordx4 v[58:61], v[58:59], off
	v_readlane_b32 s73, v251, 35
	global_load_dwordx4 v[62:65], v[62:63], off
	v_readlane_b32 s74, v251, 36
	v_readlane_b32 s75, v251, 37
	v_readlane_b32 s76, v251, 38
	v_readlane_b32 s77, v251, 39
	v_readlane_b32 s78, v251, 40
	v_readlane_b32 s79, v251, 41
	v_readlane_b32 s80, v251, 42
	v_readlane_b32 s81, v251, 43
	v_readlane_b32 s82, v251, 44
	v_readlane_b32 s83, v251, 45
	v_readlane_b32 s86, v251, 48
	v_readlane_b32 s87, v251, 49
	s_mov_b64 s[2:3], 0
	s_waitcnt vmcnt(0)
	v_cvt_pk_bf16_f32 v72, v2, v6
	v_cvt_pk_bf16_f32 v2, v5, v9
	v_cvt_pk_bf16_f32 v73, v10, v14
	v_add_co_u32_e32 v10, vcc, s0, v66
	v_cvt_pk_bf16_f32 v74, v18, v22
	v_cvt_pk_bf16_f32 v75, v26, v30
	v_cvt_pk_bf16_f32 v5, v29, v33
	v_cvt_pk_bf16_f32 v76, v34, v38
	v_cvt_pk_bf16_f32 v6, v37, v41
	v_cvt_pk_bf16_f32 v77, v42, v46
	v_cvt_pk_bf16_f32 v78, v50, v54
	v_cvt_pk_bf16_f32 v79, v58, v62
	global_store_dwordx4 v[66:67], v[72:75], off sc0 sc1
	global_store_dwordx4 v[66:67], v[76:79], off offset:16 sc0 sc1
	v_cvt_pk_bf16_f32 v9, v61, v65
	v_cvt_pk_bf16_f32 v72, v3, v7
	v_cvt_pk_bf16_f32 v73, v11, v15
	v_cvt_pk_bf16_f32 v74, v19, v23
	v_cvt_pk_bf16_f32 v75, v27, v31
	v_cvt_pk_bf16_f32 v76, v35, v39
	v_cvt_pk_bf16_f32 v77, v43, v47
	v_cvt_pk_bf16_f32 v78, v51, v55
	v_cvt_pk_bf16_f32 v79, v59, v63
	global_store_dwordx4 v[66:67], v[72:75], off offset:2048 sc0 sc1
	global_store_dwordx4 v[66:67], v[76:79], off offset:2064 sc0 sc1
	v_addc_co_u32_e32 v11, vcc, 0, v67, vcc
	v_cvt_pk_bf16_f32 v72, v4, v8
	v_cvt_pk_bf16_f32 v73, v12, v16
	v_cvt_pk_bf16_f32 v74, v20, v24
	v_cvt_pk_bf16_f32 v75, v28, v32
	v_cvt_pk_bf16_f32 v3, v13, v17
	v_cvt_pk_bf16_f32 v4, v21, v25
	v_cvt_pk_bf16_f32 v76, v36, v40
	v_cvt_pk_bf16_f32 v77, v44, v48
	v_cvt_pk_bf16_f32 v78, v52, v56
	v_cvt_pk_bf16_f32 v79, v60, v64
	global_store_dwordx4 v[10:11], v[72:75], off sc0 sc1
	global_store_dwordx4 v[10:11], v[76:79], off offset:16 sc0 sc1
	v_cvt_pk_bf16_f32 v7, v45, v49
	v_cvt_pk_bf16_f32 v8, v53, v57
	global_store_dwordx4 v[10:11], v[2:5], off offset:2048 sc0 sc1
	global_store_dwordx4 v[10:11], v[6:9], off offset:2064 sc0 sc1

.LBB0_797:
	v_readlane_b32 s2, v251, 30
	v_readlane_b32 s3, v251, 31
	v_ashrrev_i32_e32 v81, 31, v0
	v_mov_b32_e32 v80, v0
	v_lshl_add_u64 v[66:67], v[66:67], 1, s[2:3]
	v_lshlrev_b64 v[80:81], 11, v[80:81]
	s_waitcnt vmcnt(0)
	v_cvt_pk_bf16_f32 v72, v62, v54
	v_cvt_pk_bf16_f32 v73, v58, v46
	v_cvt_pk_bf16_f32 v74, v50, v38
	v_cvt_pk_bf16_f32 v75, v42, v34
	v_cvt_pk_bf16_f32 v79, v14, v2
	v_lshl_add_u64 v[80:81], v[66:67], 0, v[80:81]
	v_add_u32_e32 v2, 1, v0
	v_cvt_pk_bf16_f32 v76, v30, v22
	v_cvt_pk_bf16_f32 v77, v26, v10
	v_cvt_pk_bf16_f32 v78, v18, v6
	global_store_dwordx4 v[80:81], v[72:75], off sc0 sc1
	global_store_dwordx4 v[80:81], v[76:79], off offset:16 sc0 sc1
	v_add_u32_e32 v6, 3, v0
	v_cvt_pk_bf16_f32 v72, v63, v55
	v_cvt_pk_bf16_f32 v79, v15, v3
	v_ashrrev_i32_e32 v3, 31, v2
	v_lshlrev_b64 v[2:3], 11, v[2:3]
	v_cvt_pk_bf16_f32 v73, v59, v47
	v_cvt_pk_bf16_f32 v74, v51, v39
	v_cvt_pk_bf16_f32 v75, v43, v35
	v_lshl_add_u64 v[2:3], v[66:67], 0, v[2:3]
	v_cvt_pk_bf16_f32 v76, v31, v23
	v_cvt_pk_bf16_f32 v77, v27, v11
	v_cvt_pk_bf16_f32 v78, v19, v7
	global_store_dwordx4 v[2:3], v[72:75], off sc0 sc1
	global_store_dwordx4 v[2:3], v[76:79], off offset:16 sc0 sc1
	v_add_u32_e32 v2, 2, v0
	v_ashrrev_i32_e32 v3, 31, v2
	v_ashrrev_i32_e32 v7, 31, v6
	v_lshlrev_b64 v[2:3], 11, v[2:3]
	v_lshlrev_b64 v[6:7], 11, v[6:7]
	v_cvt_pk_bf16_f32 v72, v64, v56
	v_cvt_pk_bf16_f32 v73, v60, v48
	v_cvt_pk_bf16_f32 v74, v52, v40
	v_cvt_pk_bf16_f32 v75, v44, v36
	v_lshl_add_u64 v[2:3], v[66:67], 0, v[2:3]
	v_cvt_pk_bf16_f32 v34, v65, v57
	v_cvt_pk_bf16_f32 v35, v61, v49
	v_cvt_pk_bf16_f32 v36, v53, v41
	v_cvt_pk_bf16_f32 v37, v45, v37
	v_lshl_add_u64 v[6:7], v[66:67], 0, v[6:7]
	v_cvt_pk_bf16_f32 v76, v32, v24
	v_cvt_pk_bf16_f32 v77, v28, v12
	v_cvt_pk_bf16_f32 v78, v20, v8
	v_cvt_pk_bf16_f32 v79, v16, v4
	global_store_dwordx4 v[2:3], v[72:75], off sc0 sc1
	global_store_dwordx4 v[2:3], v[76:79], off offset:16 sc0 sc1
	v_cvt_pk_bf16_f32 v2, v33, v25
	v_cvt_pk_bf16_f32 v3, v29, v13
	v_cvt_pk_bf16_f32 v4, v21, v9
	v_cvt_pk_bf16_f32 v5, v17, v5
	global_store_dwordx4 v[6:7], v[34:37], off sc0 sc1
	global_store_dwordx4 v[6:7], v[2:5], off offset:16 sc0 sc1

.LBB0_799:
	s_andn2_b64 vcc, exec, s[2:3]
	s_cbranch_vccnz .LBB0_787
	s_cmpk_gt_u32 s4, 0x7ff
	s_mov_b64 s[2:3], -1
	s_cbranch_scc0 .LBB0_802
	s_and_b32 s0, s6, 0x3c0
	v_or_b32_e32 v80, s0, v69
	s_and_b32 s0, s8, 0x7fffffc0
	v_readlane_b32 s72, v251, 4
	v_add_u32_e32 v66, s0, v71
	v_lshlrev_b32_e32 v0, 2, v80
	v_readlane_b32 s84, v251, 16
	v_readlane_b32 s85, v251, 17
	v_mov_b32_e32 v67, v1
	v_lshlrev_b64 v[2:3], 12, v[66:67]
	v_lshl_add_u64 v[62:63], s[84:85], 0, v[0:1]
	v_or_b32_e32 v0, 1, v66
	v_lshlrev_b64 v[6:7], 12, v[0:1]
	v_or_b32_e32 v0, 2, v66
	v_lshlrev_b64 v[10:11], 12, v[0:1]
	v_or_b32_e32 v0, 3, v66
	v_lshlrev_b64 v[14:15], 12, v[0:1]
	v_or_b32_e32 v0, 4, v66
	v_lshlrev_b64 v[18:19], 12, v[0:1]
	v_or_b32_e32 v0, 5, v66
	v_lshlrev_b64 v[22:23], 12, v[0:1]
	v_or_b32_e32 v0, 6, v66
	v_lshlrev_b64 v[26:27], 12, v[0:1]
	v_or_b32_e32 v0, 7, v66
	v_lshlrev_b64 v[30:31], 12, v[0:1]
	v_or_b32_e32 v0, 8, v66
	v_lshlrev_b64 v[34:35], 12, v[0:1]
	v_or_b32_e32 v0, 9, v66
	v_lshlrev_b64 v[38:39], 12, v[0:1]
	v_or_b32_e32 v0, 10, v66
	v_lshlrev_b64 v[42:43], 12, v[0:1]
	v_or_b32_e32 v0, 11, v66
	v_lshlrev_b64 v[46:47], 12, v[0:1]
	v_or_b32_e32 v0, 12, v66
	v_lshlrev_b64 v[50:51], 12, v[0:1]
	v_or_b32_e32 v0, 13, v66
	v_lshlrev_b64 v[54:55], 12, v[0:1]
	v_or_b32_e32 v0, 14, v66
	v_lshlrev_b64 v[58:59], 12, v[0:1]
	v_or_b32_e32 v0, 15, v66
	v_lshl_add_u64 v[2:3], v[62:63], 0, v[2:3]
	v_lshl_add_u64 v[6:7], v[62:63], 0, v[6:7]
	v_lshl_add_u64 v[10:11], v[62:63], 0, v[10:11]
	v_lshl_add_u64 v[14:15], v[62:63], 0, v[14:15]
	v_lshl_add_u64 v[18:19], v[62:63], 0, v[18:19]
	v_lshl_add_u64 v[22:23], v[62:63], 0, v[22:23]
	v_lshl_add_u64 v[26:27], v[62:63], 0, v[26:27]
	v_lshl_add_u64 v[30:31], v[62:63], 0, v[30:31]
	v_lshlrev_b64 v[64:65], 12, v[0:1]
	global_load_dwordx4 v[2:5], v[2:3], off
	v_lshl_add_u64 v[34:35], v[62:63], 0, v[34:35]
	global_load_dwordx4 v[6:9], v[6:7], off
	v_lshl_add_u64 v[38:39], v[62:63], 0, v[38:39]
	global_load_dwordx4 v[10:13], v[10:11], off
	v_lshl_add_u64 v[42:43], v[62:63], 0, v[42:43]
	global_load_dwordx4 v[14:17], v[14:15], off
	v_lshl_add_u64 v[46:47], v[62:63], 0, v[46:47]
	global_load_dwordx4 v[18:21], v[18:19], off
	v_lshl_add_u64 v[50:51], v[62:63], 0, v[50:51]
	global_load_dwordx4 v[22:25], v[22:23], off
	v_lshl_add_u64 v[54:55], v[62:63], 0, v[54:55]
	global_load_dwordx4 v[26:29], v[26:27], off
	v_lshl_add_u64 v[58:59], v[62:63], 0, v[58:59]
	global_load_dwordx4 v[30:33], v[30:31], off
	v_lshl_add_u64 v[62:63], v[62:63], 0, v[64:65]
	global_load_dwordx4 v[34:37], v[34:35], off
	v_readlane_b32 s2, v250, 38
	global_load_dwordx4 v[38:41], v[38:39], off
	v_readlane_b32 s3, v250, 39
	global_load_dwordx4 v[42:45], v[42:43], off
	v_mul_u32_u24_e32 v0, 0xb00, v80
	global_load_dwordx4 v[46:49], v[46:47], off
	v_lshl_add_u64 v[66:67], v[66:67], 1, s[2:3]
	global_load_dwordx4 v[50:53], v[50:51], off
	v_lshlrev_b32_e32 v0, 1, v0
	global_load_dwordx4 v[54:57], v[54:55], off
	v_lshl_add_u64 v[66:67], v[66:67], 0, v[0:1]
	global_load_dwordx4 v[58:61], v[58:59], off
	s_movk_i32 s0, 0x1000
	global_load_dwordx4 v[62:65], v[62:63], off
	v_readlane_b32 s73, v251, 5
	v_readlane_b32 s74, v251, 6
	v_readlane_b32 s75, v251, 7
	v_readlane_b32 s76, v251, 8
	v_readlane_b32 s77, v251, 9
	v_readlane_b32 s78, v251, 10
	v_readlane_b32 s79, v251, 11
	v_readlane_b32 s80, v251, 12
	v_readlane_b32 s81, v251, 13
	v_readlane_b32 s82, v251, 14
	v_readlane_b32 s83, v251, 15
	v_readlane_b32 s86, v251, 18
	v_readlane_b32 s87, v251, 19
	s_mov_b64 s[2:3], 0
	s_waitcnt vmcnt(0)
	v_cvt_pk_bf16_f32 v72, v2, v6
	v_add_co_u32_e32 v2, vcc, s0, v66
	s_movk_i32 s0, 0x2000
	v_cvt_pk_bf16_f32 v73, v10, v14
	v_cvt_pk_bf16_f32 v74, v18, v22
	v_cvt_pk_bf16_f32 v75, v26, v30
	v_cvt_pk_bf16_f32 v76, v34, v38
	v_cvt_pk_bf16_f32 v6, v37, v41
	v_cvt_pk_bf16_f32 v77, v42, v46
	v_cvt_pk_bf16_f32 v78, v50, v54
	v_cvt_pk_bf16_f32 v79, v58, v62
	global_store_dwordx4 v[66:67], v[72:75], off sc0 sc1
	global_store_dwordx4 v[66:67], v[76:79], off offset:16 sc0 sc1
	s_nop 0
	v_cvt_pk_bf16_f32 v72, v3, v7
	v_cvt_pk_bf16_f32 v73, v11, v15
	v_cvt_pk_bf16_f32 v74, v19, v23
	v_cvt_pk_bf16_f32 v75, v27, v31
	v_addc_co_u32_e32 v3, vcc, 0, v67, vcc
	v_cvt_pk_bf16_f32 v76, v35, v39
	v_cvt_pk_bf16_f32 v77, v43, v47
	v_cvt_pk_bf16_f32 v78, v51, v55
	v_cvt_pk_bf16_f32 v79, v59, v63
	global_store_dwordx4 v[2:3], v[72:75], off offset:1536 sc0 sc1
	global_store_dwordx4 v[2:3], v[76:79], off offset:1552 sc0 sc1
	v_add_co_u32_e32 v2, vcc, s0, v66
	v_cvt_pk_bf16_f32 v72, v4, v8
	s_nop 0
	v_addc_co_u32_e32 v3, vcc, 0, v67, vcc
	v_cvt_pk_bf16_f32 v73, v12, v16
	v_cvt_pk_bf16_f32 v74, v20, v24
	v_cvt_pk_bf16_f32 v75, v28, v32
	v_add_co_u32_e32 v10, vcc, 0x4000, v66
	v_cvt_pk_bf16_f32 v76, v36, v40
	v_cvt_pk_bf16_f32 v77, v44, v48
	v_cvt_pk_bf16_f32 v78, v52, v56
	v_cvt_pk_bf16_f32 v79, v60, v64
	global_store_dwordx4 v[2:3], v[72:75], off offset:3072 sc0 sc1
	global_store_dwordx4 v[2:3], v[76:79], off offset:3088 sc0 sc1
	v_cvt_pk_bf16_f32 v2, v5, v9
	v_cvt_pk_bf16_f32 v3, v13, v17
	v_cvt_pk_bf16_f32 v4, v21, v25
	v_cvt_pk_bf16_f32 v5, v29, v33
	v_addc_co_u32_e32 v11, vcc, 0, v67, vcc
	v_cvt_pk_bf16_f32 v7, v45, v49
	v_cvt_pk_bf16_f32 v8, v53, v57
	v_cvt_pk_bf16_f32 v9, v61, v65
	global_store_dwordx4 v[10:11], v[2:5], off offset:512 sc0 sc1
	global_store_dwordx4 v[10:11], v[6:9], off offset:528 sc0 sc1

.LBB0_1074:
	s_andn2_saveexec_b64 s[6:7], s[6:7]
	s_cbranch_execz .LBB0_1094
	s_mov_b64 s[6:7], exec
	v_readlane_b32 s0, v251, 23
	s_nop 3
	s_cmp_lg_u32 s0, 0
	s_cbranch_scc1 .Lwo_nowb
	buffer_wbl2 sc1
.Lwo_nowb:
	s_waitcnt lgkmcnt(0)
	s_waitcnt vmcnt(0)
	v_mbcnt_lo_u32_b32 v0, s6, 0
	v_mbcnt_hi_u32_b32 v0, s7, v0
	v_cmp_eq_u32_e32 vcc, 0, v0
	s_and_saveexec_b64 s[8:9], vcc
	s_cbranch_execz .LBB0_1077
	s_bcnt1_i32_b64 s0, s[6:7]
	v_readlane_b32 s6, v250, 23
	v_mov_b32_e32 v3, s0
	v_readlane_b32 s7, v250, 24
	s_nop 4
	global_atomic_add v3, v1, v3, s[6:7] sc0

.LBB0_1115:
	s_or_b64 exec, exec, s[24:25]
	v_ashrrev_i32_e32 v55, 31, v54
	v_lshl_add_u64 v[48:49], v[56:57], 1, s[44:45]
	v_lshlrev_b64 v[28:29], 11, v[54:55]
	v_cvt_pk_bf16_f32 v44, v68, v66
	v_cvt_pk_bf16_f32 v45, v64, v80
	v_cvt_pk_bf16_f32 v46, v74, v76
	v_cvt_pk_bf16_f32 v47, v78, v50
	v_cvt_pk_bf16_f32 v91, v6, v2
	v_lshl_add_u64 v[28:29], v[48:49], 0, v[28:29]
	v_add_u32_e32 v2, 1, v54
	v_cvt_pk_bf16_f32 v88, v38, v42
	v_cvt_pk_bf16_f32 v89, v34, v26
	v_cvt_pk_bf16_f32 v90, v18, v10
	global_store_dwordx4 v[28:29], v[44:47], off sc0 sc1
	global_store_dwordx4 v[28:29], v[88:91], off offset:16 sc0 sc1
	v_cvt_pk_bf16_f32 v29, v7, v3
	v_ashrrev_i32_e32 v3, 31, v2
	v_lshlrev_b64 v[2:3], 11, v[2:3]
	v_cvt_pk_bf16_f32 v44, v69, v67
	v_cvt_pk_bf16_f32 v45, v65, v81
	v_cvt_pk_bf16_f32 v46, v75, v77
	v_cvt_pk_bf16_f32 v47, v79, v51
	v_lshl_add_u64 v[2:3], v[48:49], 0, v[2:3]
	v_cvt_pk_bf16_f32 v26, v39, v43
	v_cvt_pk_bf16_f32 v27, v35, v27
	v_cvt_pk_bf16_f32 v28, v19, v11
	global_store_dwordx4 v[2:3], v[44:47], off sc0 sc1
	global_store_dwordx4 v[2:3], v[26:29], off offset:16 sc0 sc1
	v_add_u32_e32 v2, 2, v54
	v_ashrrev_i32_e32 v3, 31, v2
	v_add_u32_e32 v6, 3, v54
	v_lshlrev_b64 v[2:3], 11, v[2:3]
	v_ashrrev_i32_e32 v7, 31, v6
	v_cvt_pk_bf16_f32 v26, v62, v60
	v_cvt_pk_bf16_f32 v27, v58, v72
	v_cvt_pk_bf16_f32 v28, v70, v40
	v_cvt_pk_bf16_f32 v29, v32, v30
	v_lshl_add_u64 v[2:3], v[48:49], 0, v[2:3]
	v_lshlrev_b64 v[6:7], 11, v[6:7]
	v_cvt_pk_bf16_f32 v34, v14, v16
	v_cvt_pk_bf16_f32 v35, v22, v24
	v_cvt_pk_bf16_f32 v36, v20, v12
	v_cvt_pk_bf16_f32 v37, v8, v4
	global_store_dwordx4 v[2:3], v[26:29], off sc0 sc1
	global_store_dwordx4 v[2:3], v[34:37], off offset:16 sc0 sc1
	v_lshl_add_u64 v[6:7], v[48:49], 0, v[6:7]
	v_cvt_pk_bf16_f32 v26, v63, v61
	v_cvt_pk_bf16_f32 v27, v59, v73
	v_cvt_pk_bf16_f32 v28, v71, v41
	v_cvt_pk_bf16_f32 v29, v33, v31
	v_cvt_pk_bf16_f32 v2, v15, v17
	v_cvt_pk_bf16_f32 v3, v23, v25
	v_cvt_pk_bf16_f32 v4, v21, v13
	v_cvt_pk_bf16_f32 v5, v9, v5
	global_store_dwordx4 v[6:7], v[26:29], off sc0 sc1
	global_store_dwordx4 v[6:7], v[2:5], off offset:16 sc0 sc1

.LBB0_1117:
	s_cmp_lt_i32 s67, s63
	s_mov_b64 s[24:25], -1
	s_cbranch_scc1 .LBB0_1127
	s_add_i32 s28, s89, s67
	s_cmpk_gt_i32 s28, 0x57f
	s_cbranch_scc0 .LBB0_1120
	s_and_b32 s0, s84, 0x3c0
	v_or_b32_e32 v76, s0, v83
	s_add_i32 s0, s83, s86
	s_and_b32 s0, s0, 0x7fffffc0
	v_add_u32_e32 v66, s0, v85
	v_lshlrev_b32_e32 v0, 2, v76
	v_lshl_add_u64 v[62:63], s[6:7], 0, v[0:1]
	v_or_b32_e32 v0, 1, v66
	v_lshlrev_b64 v[6:7], 12, v[0:1]
	v_or_b32_e32 v0, 2, v66
	v_lshlrev_b64 v[10:11], 12, v[0:1]
	v_or_b32_e32 v0, 3, v66
	v_lshlrev_b64 v[14:15], 12, v[0:1]
	v_or_b32_e32 v0, 4, v66
	v_lshlrev_b64 v[18:19], 12, v[0:1]
	v_or_b32_e32 v0, 5, v66
	v_lshlrev_b64 v[22:23], 12, v[0:1]
	v_or_b32_e32 v0, 6, v66
	v_lshlrev_b64 v[26:27], 12, v[0:1]
	v_or_b32_e32 v0, 7, v66
	v_lshlrev_b64 v[30:31], 12, v[0:1]
	v_or_b32_e32 v0, 8, v66
	v_lshlrev_b64 v[34:35], 12, v[0:1]
	v_or_b32_e32 v0, 9, v66
	v_lshlrev_b64 v[38:39], 12, v[0:1]
	v_or_b32_e32 v0, 10, v66
	v_lshlrev_b64 v[42:43], 12, v[0:1]
	v_or_b32_e32 v0, 11, v66
	v_lshlrev_b64 v[46:47], 12, v[0:1]
	v_or_b32_e32 v0, 12, v66
	v_lshlrev_b64 v[50:51], 12, v[0:1]
	v_or_b32_e32 v0, 13, v66
	v_mov_b32_e32 v67, v1
	v_lshlrev_b64 v[54:55], 12, v[0:1]
	v_or_b32_e32 v0, 14, v66
	v_lshlrev_b64 v[2:3], 12, v[66:67]
	v_lshlrev_b64 v[58:59], 12, v[0:1]
	v_or_b32_e32 v0, 15, v66
	v_lshl_add_u64 v[2:3], v[62:63], 0, v[2:3]
	v_lshl_add_u64 v[6:7], v[62:63], 0, v[6:7]
	v_lshl_add_u64 v[10:11], v[62:63], 0, v[10:11]
	v_lshl_add_u64 v[14:15], v[62:63], 0, v[14:15]
	v_lshl_add_u64 v[18:19], v[62:63], 0, v[18:19]
	v_lshl_add_u64 v[22:23], v[62:63], 0, v[22:23]
	v_lshl_add_u64 v[26:27], v[62:63], 0, v[26:27]
	v_lshl_add_u64 v[30:31], v[62:63], 0, v[30:31]
	v_lshlrev_b64 v[64:65], 12, v[0:1]
	global_load_dwordx4 v[2:5], v[2:3], off
	v_lshl_add_u64 v[34:35], v[62:63], 0, v[34:35]
	global_load_dwordx4 v[6:9], v[6:7], off
	v_lshl_add_u64 v[38:39], v[62:63], 0, v[38:39]
	global_load_dwordx4 v[10:13], v[10:11], off
	v_lshl_add_u64 v[42:43], v[62:63], 0, v[42:43]
	global_load_dwordx4 v[14:17], v[14:15], off
	v_lshl_add_u64 v[46:47], v[62:63], 0, v[46:47]
	global_load_dwordx4 v[18:21], v[18:19], off
	v_lshl_add_u64 v[50:51], v[62:63], 0, v[50:51]
	global_load_dwordx4 v[22:25], v[22:23], off
	v_lshl_add_u64 v[54:55], v[62:63], 0, v[54:55]
	global_load_dwordx4 v[26:29], v[26:27], off
	v_lshl_add_u64 v[58:59], v[62:63], 0, v[58:59]
	global_load_dwordx4 v[30:33], v[30:31], off
	v_lshl_add_u64 v[62:63], v[62:63], 0, v[64:65]
	global_load_dwordx4 v[34:37], v[34:35], off
	v_mul_u32_u24_e32 v0, 0xb00, v76
	global_load_dwordx4 v[38:41], v[38:39], off
	v_lshl_add_u64 v[74:75], v[66:67], 1, s[2:3]
	global_load_dwordx4 v[42:45], v[42:43], off
	v_lshlrev_b32_e32 v0, 1, v0
	global_load_dwordx4 v[46:49], v[46:47], off
	v_lshl_add_u64 v[74:75], v[74:75], 0, v[0:1]
	global_load_dwordx4 v[50:53], v[50:51], off
	s_mov_b64 s[24:25], 0
	global_load_dwordx4 v[54:57], v[54:55], off
	s_waitcnt vmcnt(0)
	v_cvt_pk_bf16_f32 v66, v2, v6
	global_load_dwordx4 v[58:61], v[58:59], off
	v_add_co_u32_e32 v2, vcc, s73, v74
	global_load_dwordx4 v[62:65], v[62:63], off
	v_cvt_pk_bf16_f32 v67, v10, v14
	v_cvt_pk_bf16_f32 v68, v18, v22
	v_cvt_pk_bf16_f32 v69, v26, v30
	v_cvt_pk_bf16_f32 v70, v34, v38
	v_cvt_pk_bf16_f32 v6, v37, v41
	v_cvt_pk_bf16_f32 v71, v42, v46
	v_cvt_pk_bf16_f32 v72, v50, v54
	s_waitcnt vmcnt(0)
	v_cvt_pk_bf16_f32 v73, v58, v62
	global_store_dwordx4 v[74:75], v[66:69], off sc0 sc1
	global_store_dwordx4 v[74:75], v[70:73], off offset:16 sc0 sc1
	s_nop 0
	v_cvt_pk_bf16_f32 v66, v3, v7
	v_cvt_pk_bf16_f32 v67, v11, v15
	v_cvt_pk_bf16_f32 v68, v19, v23
	v_cvt_pk_bf16_f32 v69, v27, v31
	v_addc_co_u32_e32 v3, vcc, 0, v75, vcc
	v_cvt_pk_bf16_f32 v70, v35, v39
	v_cvt_pk_bf16_f32 v71, v43, v47
	v_cvt_pk_bf16_f32 v72, v51, v55
	v_cvt_pk_bf16_f32 v73, v59, v63
	global_store_dwordx4 v[2:3], v[66:69], off offset:1536 sc0 sc1
	global_store_dwordx4 v[2:3], v[70:73], off offset:1552 sc0 sc1
	v_add_co_u32_e32 v2, vcc, s71, v74
	v_cvt_pk_bf16_f32 v66, v4, v8
	s_nop 0
	v_addc_co_u32_e32 v3, vcc, 0, v75, vcc
	v_cvt_pk_bf16_f32 v67, v12, v16
	v_cvt_pk_bf16_f32 v68, v20, v24
	v_cvt_pk_bf16_f32 v69, v28, v32
	v_add_co_u32_e32 v10, vcc, 0x4000, v74
	v_cvt_pk_bf16_f32 v70, v36, v40
	v_cvt_pk_bf16_f32 v71, v44, v48
	v_cvt_pk_bf16_f32 v72, v52, v56
	v_cvt_pk_bf16_f32 v73, v60, v64
	global_store_dwordx4 v[2:3], v[66:69], off offset:3072 sc0 sc1
	global_store_dwordx4 v[2:3], v[70:73], off offset:3088 sc0 sc1
	v_cvt_pk_bf16_f32 v2, v5, v9
	v_cvt_pk_bf16_f32 v3, v13, v17
	v_cvt_pk_bf16_f32 v4, v21, v25
	v_cvt_pk_bf16_f32 v5, v29, v33
	v_addc_co_u32_e32 v11, vcc, 0, v75, vcc
	v_cvt_pk_bf16_f32 v7, v45, v49
	v_cvt_pk_bf16_f32 v8, v53, v57
	v_cvt_pk_bf16_f32 v9, v61, v65
	global_store_dwordx4 v[10:11], v[2:5], off offset:512 sc0 sc1
	global_store_dwordx4 v[10:11], v[6:9], off offset:528 sc0 sc1

.LBB0_1125:
	v_lshlrev_b32_e32 v0, 1, v0
	v_ashrrev_i32_e32 v55, 31, v54
	v_lshl_add_u64 v[48:49], s[20:21], 0, v[0:1]
	v_lshlrev_b64 v[28:29], 11, v[54:55]
	v_cvt_pk_bf16_f32 v44, v66, v64
	v_cvt_pk_bf16_f32 v45, v62, v78
	v_cvt_pk_bf16_f32 v46, v72, v74
	v_cvt_pk_bf16_f32 v47, v76, v50
	v_cvt_pk_bf16_f32 v91, v6, v2
	v_lshl_add_u64 v[28:29], v[48:49], 0, v[28:29]
	v_or_b32_e32 v2, 1, v54
	v_cvt_pk_bf16_f32 v88, v38, v42
	v_cvt_pk_bf16_f32 v89, v34, v26
	v_cvt_pk_bf16_f32 v90, v18, v10
	global_store_dwordx4 v[28:29], v[44:47], off sc0 sc1
	global_store_dwordx4 v[28:29], v[88:91], off offset:16 sc0 sc1
	v_cvt_pk_bf16_f32 v29, v7, v3
	v_ashrrev_i32_e32 v3, 31, v2
	v_lshlrev_b64 v[2:3], 11, v[2:3]
	v_cvt_pk_bf16_f32 v44, v67, v65
	v_cvt_pk_bf16_f32 v45, v63, v79
	v_cvt_pk_bf16_f32 v46, v73, v75
	v_cvt_pk_bf16_f32 v47, v77, v51
	v_lshl_add_u64 v[2:3], v[48:49], 0, v[2:3]
	v_cvt_pk_bf16_f32 v26, v39, v43
	v_cvt_pk_bf16_f32 v27, v35, v27
	v_cvt_pk_bf16_f32 v28, v19, v11
	global_store_dwordx4 v[2:3], v[44:47], off sc0 sc1
	global_store_dwordx4 v[2:3], v[26:29], off offset:16 sc0 sc1
	v_or_b32_e32 v2, 2, v54
	v_ashrrev_i32_e32 v3, 31, v2
	v_or_b32_e32 v6, 3, v54
	v_lshlrev_b64 v[2:3], 11, v[2:3]
	v_ashrrev_i32_e32 v7, 31, v6
	v_cvt_pk_bf16_f32 v26, v60, v58
	v_cvt_pk_bf16_f32 v27, v56, v70
	v_cvt_pk_bf16_f32 v28, v68, v40
	v_cvt_pk_bf16_f32 v29, v32, v30
	v_lshl_add_u64 v[2:3], v[48:49], 0, v[2:3]
	v_lshlrev_b64 v[6:7], 11, v[6:7]
	v_cvt_pk_bf16_f32 v34, v14, v16
	v_cvt_pk_bf16_f32 v35, v22, v24
	v_cvt_pk_bf16_f32 v36, v20, v12
	v_cvt_pk_bf16_f32 v37, v8, v4
	global_store_dwordx4 v[2:3], v[26:29], off sc0 sc1
	global_store_dwordx4 v[2:3], v[34:37], off offset:16 sc0 sc1
	v_lshl_add_u64 v[6:7], v[48:49], 0, v[6:7]
	v_cvt_pk_bf16_f32 v26, v61, v59
	v_cvt_pk_bf16_f32 v27, v57, v71
	v_cvt_pk_bf16_f32 v28, v69, v41
	v_cvt_pk_bf16_f32 v29, v33, v31
	v_cvt_pk_bf16_f32 v2, v15, v17
	v_cvt_pk_bf16_f32 v3, v23, v25
	v_cvt_pk_bf16_f32 v4, v21, v13
	v_cvt_pk_bf16_f32 v5, v9, v5
	global_store_dwordx4 v[6:7], v[26:29], off sc0 sc1
	global_store_dwordx4 v[6:7], v[2:5], off offset:16 sc0 sc1

.LBB0_1127:
	s_andn2_b64 vcc, exec, s[24:25]
	s_cbranch_vccnz .LBB0_1116
	s_andn2_b64 vcc, exec, s[76:77]
	s_mov_b64 s[24:25], -1
	s_cbranch_vccnz .LBB0_1138
	s_cmpk_gt_i32 s67, 0x17f
	s_cbranch_scc0 .LBB0_1131
	s_and_b32 s0, s84, 0x3c0
	v_or_b32_e32 v76, s0, v83
	s_and_b32 s0, s86, 0x7fffffc0
	v_add_u32_e32 v66, s0, v86
	v_lshlrev_b32_e32 v0, 2, v76
	v_lshl_add_u64 v[62:63], s[34:35], 0, v[0:1]
	v_or_b32_e32 v0, 1, v66
	v_lshlrev_b64 v[6:7], 12, v[0:1]
	v_or_b32_e32 v0, 2, v66
	v_lshlrev_b64 v[10:11], 12, v[0:1]
	v_or_b32_e32 v0, 3, v66
	v_lshlrev_b64 v[14:15], 12, v[0:1]
	v_or_b32_e32 v0, 4, v66
	v_lshlrev_b64 v[18:19], 12, v[0:1]
	v_or_b32_e32 v0, 5, v66
	v_lshlrev_b64 v[22:23], 12, v[0:1]
	v_or_b32_e32 v0, 6, v66
	v_lshlrev_b64 v[26:27], 12, v[0:1]
	v_or_b32_e32 v0, 7, v66
	v_lshlrev_b64 v[30:31], 12, v[0:1]
	v_or_b32_e32 v0, 8, v66
	v_lshlrev_b64 v[34:35], 12, v[0:1]
	v_or_b32_e32 v0, 9, v66
	v_lshlrev_b64 v[38:39], 12, v[0:1]
	v_or_b32_e32 v0, 10, v66
	v_lshlrev_b64 v[42:43], 12, v[0:1]
	v_or_b32_e32 v0, 11, v66
	v_lshlrev_b64 v[46:47], 12, v[0:1]
	v_or_b32_e32 v0, 12, v66
	v_lshlrev_b64 v[50:51], 12, v[0:1]
	v_or_b32_e32 v0, 13, v66
	v_mov_b32_e32 v67, v1
	v_lshlrev_b64 v[54:55], 12, v[0:1]
	v_or_b32_e32 v0, 14, v66
	v_lshlrev_b64 v[2:3], 12, v[66:67]
	v_lshlrev_b64 v[58:59], 12, v[0:1]
	v_or_b32_e32 v0, 15, v66
	v_lshl_add_u64 v[2:3], v[62:63], 0, v[2:3]
	v_lshl_add_u64 v[6:7], v[62:63], 0, v[6:7]
	v_lshl_add_u64 v[10:11], v[62:63], 0, v[10:11]
	v_lshl_add_u64 v[14:15], v[62:63], 0, v[14:15]
	v_lshl_add_u64 v[18:19], v[62:63], 0, v[18:19]
	v_lshl_add_u64 v[22:23], v[62:63], 0, v[22:23]
	v_lshl_add_u64 v[26:27], v[62:63], 0, v[26:27]
	v_lshl_add_u64 v[30:31], v[62:63], 0, v[30:31]
	v_lshlrev_b64 v[64:65], 12, v[0:1]
	global_load_dwordx4 v[2:5], v[2:3], off
	v_lshl_add_u64 v[34:35], v[62:63], 0, v[34:35]
	global_load_dwordx4 v[6:9], v[6:7], off
	v_lshl_add_u64 v[38:39], v[62:63], 0, v[38:39]
	global_load_dwordx4 v[10:13], v[10:11], off
	v_lshl_add_u64 v[42:43], v[62:63], 0, v[42:43]
	global_load_dwordx4 v[14:17], v[14:15], off
	v_lshl_add_u64 v[46:47], v[62:63], 0, v[46:47]
	global_load_dwordx4 v[18:21], v[18:19], off
	v_lshl_add_u64 v[50:51], v[62:63], 0, v[50:51]
	global_load_dwordx4 v[22:25], v[22:23], off
	v_lshl_add_u64 v[54:55], v[62:63], 0, v[54:55]
	global_load_dwordx4 v[26:29], v[26:27], off
	v_lshl_add_u64 v[58:59], v[62:63], 0, v[58:59]
	global_load_dwordx4 v[30:33], v[30:31], off
	v_lshl_add_u64 v[62:63], v[62:63], 0, v[64:65]
	global_load_dwordx4 v[34:37], v[34:35], off
	v_lshl_add_u64 v[74:75], v[66:67], 1, s[30:31]
	global_load_dwordx4 v[38:41], v[38:39], off
	v_lshlrev_b32_e32 v0, 11, v76
	global_load_dwordx4 v[42:45], v[42:43], off
	v_lshl_add_u64 v[74:75], v[74:75], 0, v[0:1]
	global_load_dwordx4 v[46:49], v[46:47], off
	s_mov_b64 s[24:25], 0
	global_load_dwordx4 v[50:53], v[50:51], off
	s_waitcnt vmcnt(0)
	v_cvt_pk_bf16_f32 v66, v2, v6
	global_load_dwordx4 v[54:57], v[54:55], off
	v_cvt_pk_bf16_f32 v2, v5, v9
	global_load_dwordx4 v[58:61], v[58:59], off
	v_cvt_pk_bf16_f32 v67, v10, v14
	global_load_dwordx4 v[62:65], v[62:63], off
	v_add_co_u32_e32 v10, vcc, s73, v74
	v_cvt_pk_bf16_f32 v68, v18, v22
	v_cvt_pk_bf16_f32 v69, v26, v30
	v_cvt_pk_bf16_f32 v5, v29, v33
	v_cvt_pk_bf16_f32 v70, v34, v38
	v_cvt_pk_bf16_f32 v6, v37, v41
	v_cvt_pk_bf16_f32 v71, v42, v46
	s_waitcnt vmcnt(0)
	v_cvt_pk_bf16_f32 v72, v50, v54
	v_cvt_pk_bf16_f32 v73, v58, v62
	global_store_dwordx4 v[74:75], v[66:69], off sc0 sc1
	global_store_dwordx4 v[74:75], v[70:73], off offset:16 sc0 sc1
	v_cvt_pk_bf16_f32 v9, v61, v65
	v_cvt_pk_bf16_f32 v66, v3, v7
	v_cvt_pk_bf16_f32 v67, v11, v15
	v_cvt_pk_bf16_f32 v68, v19, v23
	v_cvt_pk_bf16_f32 v69, v27, v31
	v_cvt_pk_bf16_f32 v70, v35, v39
	v_cvt_pk_bf16_f32 v71, v43, v47
	v_cvt_pk_bf16_f32 v72, v51, v55
	v_cvt_pk_bf16_f32 v73, v59, v63
	global_store_dwordx4 v[74:75], v[66:69], off offset:2048 sc0 sc1
	global_store_dwordx4 v[74:75], v[70:73], off offset:2064 sc0 sc1
	v_addc_co_u32_e32 v11, vcc, 0, v75, vcc
	v_cvt_pk_bf16_f32 v66, v4, v8
	v_cvt_pk_bf16_f32 v67, v12, v16
	v_cvt_pk_bf16_f32 v68, v20, v24
	v_cvt_pk_bf16_f32 v69, v28, v32
	v_cvt_pk_bf16_f32 v3, v13, v17
	v_cvt_pk_bf16_f32 v4, v21, v25
	v_cvt_pk_bf16_f32 v70, v36, v40
	v_cvt_pk_bf16_f32 v71, v44, v48
	v_cvt_pk_bf16_f32 v72, v52, v56
	v_cvt_pk_bf16_f32 v73, v60, v64
	global_store_dwordx4 v[10:11], v[66:69], off sc0 sc1
	global_store_dwordx4 v[10:11], v[70:73], off offset:16 sc0 sc1
	v_cvt_pk_bf16_f32 v7, v45, v49
	v_cvt_pk_bf16_f32 v8, v53, v57
	global_store_dwordx4 v[10:11], v[2:5], off offset:2048 sc0 sc1
	global_store_dwordx4 v[10:11], v[6:9], off offset:2064 sc0 sc1

.LBB0_1136:
	v_ashrrev_i32_e32 v55, 31, v54
	v_lshl_add_u64 v[48:49], v[56:57], 1, s[64:65]
	v_lshlrev_b64 v[28:29], 11, v[54:55]
	v_cvt_pk_bf16_f32 v44, v68, v66
	v_cvt_pk_bf16_f32 v45, v64, v80
	v_cvt_pk_bf16_f32 v46, v74, v76
	v_cvt_pk_bf16_f32 v47, v78, v50
	v_cvt_pk_bf16_f32 v91, v6, v2
	v_lshl_add_u64 v[28:29], v[48:49], 0, v[28:29]
	v_add_u32_e32 v2, 1, v54
	v_cvt_pk_bf16_f32 v88, v38, v42
	v_cvt_pk_bf16_f32 v89, v34, v26
	v_cvt_pk_bf16_f32 v90, v18, v10
	global_store_dwordx4 v[28:29], v[44:47], off sc0 sc1
	global_store_dwordx4 v[28:29], v[88:91], off offset:16 sc0 sc1
	v_cvt_pk_bf16_f32 v29, v7, v3
	v_ashrrev_i32_e32 v3, 31, v2
	v_lshlrev_b64 v[2:3], 11, v[2:3]
	v_cvt_pk_bf16_f32 v44, v69, v67
	v_cvt_pk_bf16_f32 v45, v65, v81
	v_cvt_pk_bf16_f32 v46, v75, v77
	v_cvt_pk_bf16_f32 v47, v79, v51
	v_lshl_add_u64 v[2:3], v[48:49], 0, v[2:3]
	v_cvt_pk_bf16_f32 v26, v39, v43
	v_cvt_pk_bf16_f32 v27, v35, v27
	v_cvt_pk_bf16_f32 v28, v19, v11
	global_store_dwordx4 v[2:3], v[44:47], off sc0 sc1
	global_store_dwordx4 v[2:3], v[26:29], off offset:16 sc0 sc1
	v_add_u32_e32 v2, 2, v54
	v_ashrrev_i32_e32 v3, 31, v2
	v_add_u32_e32 v6, 3, v54
	v_lshlrev_b64 v[2:3], 11, v[2:3]
	v_ashrrev_i32_e32 v7, 31, v6
	v_cvt_pk_bf16_f32 v26, v62, v60
	v_cvt_pk_bf16_f32 v27, v58, v72
	v_cvt_pk_bf16_f32 v28, v70, v40
	v_cvt_pk_bf16_f32 v29, v32, v30
	v_lshl_add_u64 v[2:3], v[48:49], 0, v[2:3]
	v_lshlrev_b64 v[6:7], 11, v[6:7]
	v_cvt_pk_bf16_f32 v34, v14, v16
	v_cvt_pk_bf16_f32 v35, v22, v24
	v_cvt_pk_bf16_f32 v36, v20, v12
	v_cvt_pk_bf16_f32 v37, v8, v4
	global_store_dwordx4 v[2:3], v[26:29], off sc0 sc1
	global_store_dwordx4 v[2:3], v[34:37], off offset:16 sc0 sc1
	v_lshl_add_u64 v[6:7], v[48:49], 0, v[6:7]
	v_cvt_pk_bf16_f32 v26, v63, v61
	v_cvt_pk_bf16_f32 v27, v59, v73
	v_cvt_pk_bf16_f32 v28, v71, v41
	v_cvt_pk_bf16_f32 v29, v33, v31
	v_cvt_pk_bf16_f32 v2, v15, v17
	v_cvt_pk_bf16_f32 v3, v23, v25
	v_cvt_pk_bf16_f32 v4, v21, v13
	v_cvt_pk_bf16_f32 v5, v9, v5
	global_store_dwordx4 v[6:7], v[26:29], off sc0 sc1
	global_store_dwordx4 v[6:7], v[2:5], off offset:16 sc0 sc1

.LBB0_1138:
	s_andn2_b64 vcc, exec, s[24:25]
	s_cbranch_vccnz .LBB0_1116
	s_cmpk_gt_i32 s67, 0xbf
	s_mov_b64 s[24:25], -1
	s_cbranch_scc0 .LBB0_1153
	s_cmpk_gt_u32 s67, 0x14f
	s_cbranch_scc0 .LBB0_1148
	s_cmpk_gt_u32 s67, 0x1cf
	s_cbranch_scc0 .LBB0_1143
	s_and_b32 s0, s84, 0x3c0
	v_or_b32_e32 v76, s0, v83
	s_and_b32 s0, s86, 0x7fffffc0
	v_add_u32_e32 v66, s0, v87
	v_lshlrev_b32_e32 v0, 2, v76
	v_lshl_add_u64 v[62:63], s[80:81], 0, v[0:1]
	v_or_b32_e32 v0, 1, v66
	v_lshlrev_b64 v[6:7], 12, v[0:1]
	v_or_b32_e32 v0, 2, v66
	v_lshlrev_b64 v[10:11], 12, v[0:1]
	v_or_b32_e32 v0, 3, v66
	v_lshlrev_b64 v[14:15], 12, v[0:1]
	v_or_b32_e32 v0, 4, v66
	v_lshlrev_b64 v[18:19], 12, v[0:1]
	v_or_b32_e32 v0, 5, v66
	v_lshlrev_b64 v[22:23], 12, v[0:1]
	v_or_b32_e32 v0, 6, v66
	v_lshlrev_b64 v[26:27], 12, v[0:1]
	v_or_b32_e32 v0, 7, v66
	v_lshlrev_b64 v[30:31], 12, v[0:1]
	v_or_b32_e32 v0, 8, v66
	v_lshlrev_b64 v[34:35], 12, v[0:1]
	v_or_b32_e32 v0, 9, v66
	v_lshlrev_b64 v[38:39], 12, v[0:1]
	v_or_b32_e32 v0, 10, v66
	v_lshlrev_b64 v[42:43], 12, v[0:1]
	v_or_b32_e32 v0, 11, v66
	v_lshlrev_b64 v[46:47], 12, v[0:1]
	v_or_b32_e32 v0, 12, v66
	v_lshlrev_b64 v[50:51], 12, v[0:1]
	v_or_b32_e32 v0, 13, v66
	v_mov_b32_e32 v67, v1
	v_lshlrev_b64 v[54:55], 12, v[0:1]
	v_or_b32_e32 v0, 14, v66
	v_lshlrev_b64 v[2:3], 12, v[66:67]
	v_lshlrev_b64 v[58:59], 12, v[0:1]
	v_or_b32_e32 v0, 15, v66
	v_lshl_add_u64 v[2:3], v[62:63], 0, v[2:3]
	v_lshl_add_u64 v[6:7], v[62:63], 0, v[6:7]
	v_lshl_add_u64 v[10:11], v[62:63], 0, v[10:11]
	v_lshl_add_u64 v[14:15], v[62:63], 0, v[14:15]
	v_lshl_add_u64 v[18:19], v[62:63], 0, v[18:19]
	v_lshl_add_u64 v[22:23], v[62:63], 0, v[22:23]
	v_lshl_add_u64 v[26:27], v[62:63], 0, v[26:27]
	v_lshl_add_u64 v[30:31], v[62:63], 0, v[30:31]
	v_lshlrev_b64 v[64:65], 12, v[0:1]
	global_load_dwordx4 v[2:5], v[2:3], off
	v_lshl_add_u64 v[34:35], v[62:63], 0, v[34:35]
	global_load_dwordx4 v[6:9], v[6:7], off
	v_lshl_add_u64 v[38:39], v[62:63], 0, v[38:39]
	global_load_dwordx4 v[10:13], v[10:11], off
	v_lshl_add_u64 v[42:43], v[62:63], 0, v[42:43]
	global_load_dwordx4 v[14:17], v[14:15], off
	v_lshl_add_u64 v[46:47], v[62:63], 0, v[46:47]
	global_load_dwordx4 v[18:21], v[18:19], off
	v_lshl_add_u64 v[50:51], v[62:63], 0, v[50:51]
	global_load_dwordx4 v[22:25], v[22:23], off
	v_lshl_add_u64 v[54:55], v[62:63], 0, v[54:55]
	global_load_dwordx4 v[26:29], v[26:27], off
	v_lshl_add_u64 v[58:59], v[62:63], 0, v[58:59]
	global_load_dwordx4 v[30:33], v[30:31], off
	v_lshl_add_u64 v[62:63], v[62:63], 0, v[64:65]
	global_load_dwordx4 v[34:37], v[34:35], off
	v_lshl_add_u64 v[74:75], v[66:67], 1, s[78:79]
	global_load_dwordx4 v[38:41], v[38:39], off
	v_lshlrev_b32_e32 v0, 11, v76
	global_load_dwordx4 v[42:45], v[42:43], off
	v_lshl_add_u64 v[74:75], v[74:75], 0, v[0:1]
	global_load_dwordx4 v[46:49], v[46:47], off
	s_mov_b64 s[24:25], 0
	global_load_dwordx4 v[50:53], v[50:51], off
	s_waitcnt vmcnt(0)
	v_cvt_pk_bf16_f32 v66, v2, v6
	global_load_dwordx4 v[54:57], v[54:55], off
	v_cvt_pk_bf16_f32 v2, v5, v9
	global_load_dwordx4 v[58:61], v[58:59], off
	v_cvt_pk_bf16_f32 v67, v10, v14
	global_load_dwordx4 v[62:65], v[62:63], off
	v_add_co_u32_e32 v10, vcc, s73, v74
	v_cvt_pk_bf16_f32 v68, v18, v22
	v_cvt_pk_bf16_f32 v69, v26, v30
	v_cvt_pk_bf16_f32 v5, v29, v33
	v_cvt_pk_bf16_f32 v70, v34, v38
	v_cvt_pk_bf16_f32 v6, v37, v41
	v_cvt_pk_bf16_f32 v71, v42, v46
	s_waitcnt vmcnt(0)
	v_cvt_pk_bf16_f32 v72, v50, v54
	v_cvt_pk_bf16_f32 v73, v58, v62
	global_store_dwordx4 v[74:75], v[66:69], off sc0 sc1
	global_store_dwordx4 v[74:75], v[70:73], off offset:16 sc0 sc1
	v_cvt_pk_bf16_f32 v9, v61, v65
	v_cvt_pk_bf16_f32 v66, v3, v7
	v_cvt_pk_bf16_f32 v67, v11, v15
	v_cvt_pk_bf16_f32 v68, v19, v23
	v_cvt_pk_bf16_f32 v69, v27, v31
	v_cvt_pk_bf16_f32 v70, v35, v39
	v_cvt_pk_bf16_f32 v71, v43, v47
	v_cvt_pk_bf16_f32 v72, v51, v55
	v_cvt_pk_bf16_f32 v73, v59, v63
	global_store_dwordx4 v[74:75], v[66:69], off offset:2048 sc0 sc1
	global_store_dwordx4 v[74:75], v[70:73], off offset:2064 sc0 sc1
	v_addc_co_u32_e32 v11, vcc, 0, v75, vcc
	v_cvt_pk_bf16_f32 v66, v4, v8
	v_cvt_pk_bf16_f32 v67, v12, v16
	v_cvt_pk_bf16_f32 v68, v20, v24
	v_cvt_pk_bf16_f32 v69, v28, v32
	v_cvt_pk_bf16_f32 v3, v13, v17
	v_cvt_pk_bf16_f32 v4, v21, v25
	v_cvt_pk_bf16_f32 v70, v36, v40
	v_cvt_pk_bf16_f32 v71, v44, v48
	v_cvt_pk_bf16_f32 v72, v52, v56
	v_cvt_pk_bf16_f32 v73, v60, v64
	global_store_dwordx4 v[10:11], v[66:69], off sc0 sc1
	global_store_dwordx4 v[10:11], v[70:73], off offset:16 sc0 sc1
	v_cvt_pk_bf16_f32 v7, v45, v49
	v_cvt_pk_bf16_f32 v8, v53, v57
	global_store_dwordx4 v[10:11], v[2:5], off offset:2048 sc0 sc1
	global_store_dwordx4 v[10:11], v[6:9], off offset:2064 sc0 sc1

.LBB0_1146:
	v_lshlrev_b32_e32 v0, 1, v0
	v_lshl_add_u64 v[76:77], s[94:95], 0, v[0:1]
	v_lshlrev_b32_e32 v0, 9, v66
	s_waitcnt vmcnt(0)
	v_cvt_pk_bf16_f32 v68, v2, v6
	v_cvt_pk_bf16_f32 v69, v10, v14
	v_cvt_pk_bf16_f32 v70, v18, v22
	v_cvt_pk_bf16_f32 v71, v26, v30
	v_lshl_add_u64 v[76:77], v[76:77], 0, v[0:1]
	v_cvt_pk_bf16_f32 v72, v34, v38
	v_cvt_pk_bf16_f32 v73, v42, v46
	v_cvt_pk_bf16_f32 v74, v50, v54
	v_cvt_pk_bf16_f32 v75, v58, v62
	global_store_dwordx4 v[76:77], v[68:71], off sc0 sc1
	global_store_dwordx4 v[76:77], v[72:75], off offset:16 sc0 sc1
	v_cvt_pk_bf16_f32 v66, v3, v7
	v_cvt_pk_bf16_f32 v67, v11, v15
	v_cvt_pk_bf16_f32 v68, v19, v23
	v_cvt_pk_bf16_f32 v69, v27, v31
	v_cvt_pk_bf16_f32 v70, v35, v39
	v_cvt_pk_bf16_f32 v71, v43, v47
	v_cvt_pk_bf16_f32 v72, v51, v55
	v_cvt_pk_bf16_f32 v73, v59, v63
	global_store_dwordx4 v[76:77], v[66:69], off offset:512 sc0 sc1
	global_store_dwordx4 v[76:77], v[70:73], off offset:528 sc0 sc1
	v_cvt_pk_bf16_f32 v2, v5, v9
	v_cvt_pk_bf16_f32 v66, v4, v8
	v_cvt_pk_bf16_f32 v67, v12, v16
	v_cvt_pk_bf16_f32 v68, v20, v24
	v_cvt_pk_bf16_f32 v69, v28, v32
	v_cvt_pk_bf16_f32 v3, v13, v17
	v_cvt_pk_bf16_f32 v4, v21, v25
	v_cvt_pk_bf16_f32 v5, v29, v33
	v_cvt_pk_bf16_f32 v70, v36, v40
	v_cvt_pk_bf16_f32 v71, v44, v48
	v_cvt_pk_bf16_f32 v72, v52, v56
	v_cvt_pk_bf16_f32 v73, v60, v64
	global_store_dwordx4 v[76:77], v[66:69], off offset:1024 sc0 sc1
	global_store_dwordx4 v[76:77], v[70:73], off offset:1040 sc0 sc1
	v_cvt_pk_bf16_f32 v6, v37, v41
	v_cvt_pk_bf16_f32 v7, v45, v49
	v_cvt_pk_bf16_f32 v8, v53, v57
	v_cvt_pk_bf16_f32 v9, v61, v65
	global_store_dwordx4 v[76:77], v[2:5], off offset:1536 sc0 sc1
	global_store_dwordx4 v[76:77], v[6:9], off offset:1552 sc0 sc1

.LBB0_1151:
	v_lshlrev_b32_e32 v0, 1, v67
	v_lshl_add_u64 v[76:77], s[14:15], 0, v[0:1]
	v_mul_u32_u24_e32 v0, 0x180, v66
	v_lshlrev_b32_e32 v0, 1, v0
	s_waitcnt vmcnt(0)
	v_cvt_pk_bf16_f32 v68, v2, v6
	v_cvt_pk_bf16_f32 v69, v10, v14
	v_cvt_pk_bf16_f32 v70, v18, v22
	v_cvt_pk_bf16_f32 v71, v26, v30
	v_lshl_add_u64 v[76:77], v[76:77], 0, v[0:1]
	v_cvt_pk_bf16_f32 v72, v34, v38
	v_cvt_pk_bf16_f32 v73, v42, v46
	v_cvt_pk_bf16_f32 v74, v50, v54
	v_cvt_pk_bf16_f32 v75, v58, v62
	global_store_dwordx4 v[76:77], v[68:71], off sc0 sc1
	global_store_dwordx4 v[76:77], v[72:75], off offset:16 sc0 sc1
	v_cvt_pk_bf16_f32 v66, v3, v7
	v_cvt_pk_bf16_f32 v67, v11, v15
	v_cvt_pk_bf16_f32 v68, v19, v23
	v_cvt_pk_bf16_f32 v69, v27, v31
	v_cvt_pk_bf16_f32 v70, v35, v39
	v_cvt_pk_bf16_f32 v71, v43, v47
	v_cvt_pk_bf16_f32 v72, v51, v55
	v_cvt_pk_bf16_f32 v73, v59, v63
	global_store_dwordx4 v[76:77], v[66:69], off offset:768 sc0 sc1
	global_store_dwordx4 v[76:77], v[70:73], off offset:784 sc0 sc1
	v_cvt_pk_bf16_f32 v2, v5, v9
	v_cvt_pk_bf16_f32 v66, v4, v8
	v_cvt_pk_bf16_f32 v67, v12, v16
	v_cvt_pk_bf16_f32 v68, v20, v24
	v_cvt_pk_bf16_f32 v69, v28, v32
	v_cvt_pk_bf16_f32 v3, v13, v17
	v_cvt_pk_bf16_f32 v4, v21, v25
	v_cvt_pk_bf16_f32 v5, v29, v33
	v_cvt_pk_bf16_f32 v70, v36, v40
	v_cvt_pk_bf16_f32 v71, v44, v48
	v_cvt_pk_bf16_f32 v72, v52, v56
	v_cvt_pk_bf16_f32 v73, v60, v64
	global_store_dwordx4 v[76:77], v[66:69], off offset:1536 sc0 sc1
	global_store_dwordx4 v[76:77], v[70:73], off offset:1552 sc0 sc1
	v_cvt_pk_bf16_f32 v6, v37, v41
	v_cvt_pk_bf16_f32 v7, v45, v49
	v_cvt_pk_bf16_f32 v8, v53, v57
	v_cvt_pk_bf16_f32 v9, v61, v65
	global_store_dwordx4 v[76:77], v[2:5], off offset:2304 sc0 sc1
	global_store_dwordx4 v[76:77], v[6:9], off offset:2320 sc0 sc1

.LBB0_1170:
	s_cmp_lt_i32 s51, s34
	s_mov_b64 s[24:25], -1
	s_cbranch_scc1 .LBB0_1180
	s_add_i32 s28, s88, s51
	s_cmpk_gt_i32 s28, 0x57f
	s_cbranch_scc0 .LBB0_1173
	s_and_b32 s0, s83, 0x3c0
	v_or_b32_e32 v76, s0, v83
	s_add_i32 s0, s82, s85
	s_and_b32 s0, s0, 0x7fffffc0
	v_add_u32_e32 v66, s0, v84
	v_lshlrev_b32_e32 v0, 2, v76
	v_lshl_add_u64 v[62:63], s[6:7], 0, v[0:1]
	v_or_b32_e32 v0, 1, v66
	v_lshlrev_b64 v[6:7], 12, v[0:1]
	v_or_b32_e32 v0, 2, v66
	v_lshlrev_b64 v[10:11], 12, v[0:1]
	v_or_b32_e32 v0, 3, v66
	v_lshlrev_b64 v[14:15], 12, v[0:1]
	v_or_b32_e32 v0, 4, v66
	v_lshlrev_b64 v[18:19], 12, v[0:1]
	v_or_b32_e32 v0, 5, v66
	v_lshlrev_b64 v[22:23], 12, v[0:1]
	v_or_b32_e32 v0, 6, v66
	v_lshlrev_b64 v[26:27], 12, v[0:1]
	v_or_b32_e32 v0, 7, v66
	v_lshlrev_b64 v[30:31], 12, v[0:1]
	v_or_b32_e32 v0, 8, v66
	v_lshlrev_b64 v[34:35], 12, v[0:1]
	v_or_b32_e32 v0, 9, v66
	v_lshlrev_b64 v[38:39], 12, v[0:1]
	v_or_b32_e32 v0, 10, v66
	v_lshlrev_b64 v[42:43], 12, v[0:1]
	v_or_b32_e32 v0, 11, v66
	v_lshlrev_b64 v[46:47], 12, v[0:1]
	v_or_b32_e32 v0, 12, v66
	v_lshlrev_b64 v[50:51], 12, v[0:1]
	v_or_b32_e32 v0, 13, v66
	v_mov_b32_e32 v67, v1
	v_lshlrev_b64 v[54:55], 12, v[0:1]
	v_or_b32_e32 v0, 14, v66
	v_lshlrev_b64 v[2:3], 12, v[66:67]
	v_lshlrev_b64 v[58:59], 12, v[0:1]
	v_or_b32_e32 v0, 15, v66
	v_lshl_add_u64 v[2:3], v[62:63], 0, v[2:3]
	v_lshl_add_u64 v[6:7], v[62:63], 0, v[6:7]
	v_lshl_add_u64 v[10:11], v[62:63], 0, v[10:11]
	v_lshl_add_u64 v[14:15], v[62:63], 0, v[14:15]
	v_lshl_add_u64 v[18:19], v[62:63], 0, v[18:19]
	v_lshl_add_u64 v[22:23], v[62:63], 0, v[22:23]
	v_lshl_add_u64 v[26:27], v[62:63], 0, v[26:27]
	v_lshl_add_u64 v[30:31], v[62:63], 0, v[30:31]
	v_lshlrev_b64 v[64:65], 12, v[0:1]
	global_load_dwordx4 v[2:5], v[2:3], off
	v_lshl_add_u64 v[34:35], v[62:63], 0, v[34:35]
	global_load_dwordx4 v[6:9], v[6:7], off
	v_lshl_add_u64 v[38:39], v[62:63], 0, v[38:39]
	global_load_dwordx4 v[10:13], v[10:11], off
	v_lshl_add_u64 v[42:43], v[62:63], 0, v[42:43]
	global_load_dwordx4 v[14:17], v[14:15], off
	v_lshl_add_u64 v[46:47], v[62:63], 0, v[46:47]
	global_load_dwordx4 v[18:21], v[18:19], off
	v_lshl_add_u64 v[50:51], v[62:63], 0, v[50:51]
	global_load_dwordx4 v[22:25], v[22:23], off
	v_lshl_add_u64 v[54:55], v[62:63], 0, v[54:55]
	global_load_dwordx4 v[26:29], v[26:27], off
	v_lshl_add_u64 v[58:59], v[62:63], 0, v[58:59]
	global_load_dwordx4 v[30:33], v[30:31], off
	v_lshl_add_u64 v[62:63], v[62:63], 0, v[64:65]
	global_load_dwordx4 v[34:37], v[34:35], off
	v_mul_u32_u24_e32 v0, 0xb00, v76
	global_load_dwordx4 v[38:41], v[38:39], off
	v_lshl_add_u64 v[74:75], v[66:67], 1, s[2:3]
	global_load_dwordx4 v[42:45], v[42:43], off
	v_lshlrev_b32_e32 v0, 1, v0
	global_load_dwordx4 v[46:49], v[46:47], off
	v_lshl_add_u64 v[74:75], v[74:75], 0, v[0:1]
	global_load_dwordx4 v[50:53], v[50:51], off
	s_mov_b64 s[24:25], 0
	global_load_dwordx4 v[54:57], v[54:55], off
	s_waitcnt vmcnt(0)
	v_cvt_pk_bf16_f32 v66, v2, v6
	global_load_dwordx4 v[58:61], v[58:59], off
	v_add_co_u32_e32 v2, vcc, s72, v74
	global_load_dwordx4 v[62:65], v[62:63], off
	v_cvt_pk_bf16_f32 v67, v10, v14
	v_cvt_pk_bf16_f32 v68, v18, v22
	v_cvt_pk_bf16_f32 v69, v26, v30
	v_cvt_pk_bf16_f32 v70, v34, v38
	v_cvt_pk_bf16_f32 v6, v37, v41
	v_cvt_pk_bf16_f32 v71, v42, v46
	v_cvt_pk_bf16_f32 v72, v50, v54
	s_waitcnt vmcnt(0)
	v_cvt_pk_bf16_f32 v73, v58, v62
	global_store_dwordx4 v[74:75], v[66:69], off sc0 sc1
	global_store_dwordx4 v[74:75], v[70:73], off offset:16 sc0 sc1
	s_nop 0
	v_cvt_pk_bf16_f32 v66, v3, v7
	v_cvt_pk_bf16_f32 v67, v11, v15
	v_cvt_pk_bf16_f32 v68, v19, v23
	v_cvt_pk_bf16_f32 v69, v27, v31
	v_addc_co_u32_e32 v3, vcc, 0, v75, vcc
	v_cvt_pk_bf16_f32 v70, v35, v39
	v_cvt_pk_bf16_f32 v71, v43, v47
	v_cvt_pk_bf16_f32 v72, v51, v55
	v_cvt_pk_bf16_f32 v73, v59, v63
	global_store_dwordx4 v[2:3], v[66:69], off offset:1536 sc0 sc1
	global_store_dwordx4 v[2:3], v[70:73], off offset:1552 sc0 sc1
	v_add_co_u32_e32 v2, vcc, s63, v74
	v_cvt_pk_bf16_f32 v66, v4, v8
	s_nop 0
	v_addc_co_u32_e32 v3, vcc, 0, v75, vcc
	v_cvt_pk_bf16_f32 v67, v12, v16
	v_cvt_pk_bf16_f32 v68, v20, v24
	v_cvt_pk_bf16_f32 v69, v28, v32
	v_add_co_u32_e32 v10, vcc, 0x4000, v74
	v_cvt_pk_bf16_f32 v70, v36, v40
	v_cvt_pk_bf16_f32 v71, v44, v48
	v_cvt_pk_bf16_f32 v72, v52, v56
	v_cvt_pk_bf16_f32 v73, v60, v64
	global_store_dwordx4 v[2:3], v[66:69], off offset:3072 sc0 sc1
	global_store_dwordx4 v[2:3], v[70:73], off offset:3088 sc0 sc1
	v_cvt_pk_bf16_f32 v2, v5, v9
	v_cvt_pk_bf16_f32 v3, v13, v17
	v_cvt_pk_bf16_f32 v4, v21, v25
	v_cvt_pk_bf16_f32 v5, v29, v33
	v_addc_co_u32_e32 v11, vcc, 0, v75, vcc
	v_cvt_pk_bf16_f32 v7, v45, v49
	v_cvt_pk_bf16_f32 v8, v53, v57
	v_cvt_pk_bf16_f32 v9, v61, v65
	global_store_dwordx4 v[10:11], v[2:5], off offset:512 sc0 sc1
	global_store_dwordx4 v[10:11], v[6:9], off offset:528 sc0 sc1

.LBB0_1178:
	v_lshlrev_b32_e32 v0, 1, v0
	v_ashrrev_i32_e32 v55, 31, v54
	v_lshl_add_u64 v[48:49], s[64:65], 0, v[0:1]
	v_lshlrev_b64 v[28:29], 11, v[54:55]
	v_cvt_pk_bf16_f32 v44, v66, v64
	v_cvt_pk_bf16_f32 v45, v62, v78
	v_cvt_pk_bf16_f32 v46, v72, v74
	v_cvt_pk_bf16_f32 v47, v76, v50
	v_cvt_pk_bf16_f32 v91, v6, v2
	v_lshl_add_u64 v[28:29], v[48:49], 0, v[28:29]
	v_or_b32_e32 v2, 1, v54
	v_cvt_pk_bf16_f32 v88, v38, v42
	v_cvt_pk_bf16_f32 v89, v34, v26
	v_cvt_pk_bf16_f32 v90, v18, v10
	global_store_dwordx4 v[28:29], v[44:47], off sc0 sc1
	global_store_dwordx4 v[28:29], v[88:91], off offset:16 sc0 sc1
	v_cvt_pk_bf16_f32 v29, v7, v3
	v_ashrrev_i32_e32 v3, 31, v2
	v_lshlrev_b64 v[2:3], 11, v[2:3]
	v_cvt_pk_bf16_f32 v44, v67, v65
	v_cvt_pk_bf16_f32 v45, v63, v79
	v_cvt_pk_bf16_f32 v46, v73, v75
	v_cvt_pk_bf16_f32 v47, v77, v51
	v_lshl_add_u64 v[2:3], v[48:49], 0, v[2:3]
	v_cvt_pk_bf16_f32 v26, v39, v43
	v_cvt_pk_bf16_f32 v27, v35, v27
	v_cvt_pk_bf16_f32 v28, v19, v11
	global_store_dwordx4 v[2:3], v[44:47], off sc0 sc1
	global_store_dwordx4 v[2:3], v[26:29], off offset:16 sc0 sc1
	v_or_b32_e32 v2, 2, v54
	v_ashrrev_i32_e32 v3, 31, v2
	v_or_b32_e32 v6, 3, v54
	v_lshlrev_b64 v[2:3], 11, v[2:3]
	v_ashrrev_i32_e32 v7, 31, v6
	v_cvt_pk_bf16_f32 v26, v60, v58
	v_cvt_pk_bf16_f32 v27, v56, v70
	v_cvt_pk_bf16_f32 v28, v68, v40
	v_cvt_pk_bf16_f32 v29, v32, v30
	v_lshl_add_u64 v[2:3], v[48:49], 0, v[2:3]
	v_lshlrev_b64 v[6:7], 11, v[6:7]
	v_cvt_pk_bf16_f32 v34, v14, v16
	v_cvt_pk_bf16_f32 v35, v22, v24
	v_cvt_pk_bf16_f32 v36, v20, v12
	v_cvt_pk_bf16_f32 v37, v8, v4
	global_store_dwordx4 v[2:3], v[26:29], off sc0 sc1
	global_store_dwordx4 v[2:3], v[34:37], off offset:16 sc0 sc1
	v_lshl_add_u64 v[6:7], v[48:49], 0, v[6:7]
	v_cvt_pk_bf16_f32 v26, v61, v59
	v_cvt_pk_bf16_f32 v27, v57, v71
	v_cvt_pk_bf16_f32 v28, v69, v41
	v_cvt_pk_bf16_f32 v29, v33, v31
	v_cvt_pk_bf16_f32 v2, v15, v17
	v_cvt_pk_bf16_f32 v3, v23, v25
	v_cvt_pk_bf16_f32 v4, v21, v13
	v_cvt_pk_bf16_f32 v5, v9, v5
	global_store_dwordx4 v[6:7], v[26:29], off sc0 sc1
	global_store_dwordx4 v[6:7], v[2:5], off offset:16 sc0 sc1

.LBB0_1180:
	s_andn2_b64 vcc, exec, s[24:25]
	s_cbranch_vccnz .LBB0_1169
	s_andn2_b64 vcc, exec, s[76:77]
	s_mov_b64 s[24:25], -1
	s_cbranch_vccnz .LBB0_1191
	s_cmpk_gt_i32 s51, 0x17f
	s_cbranch_scc0 .LBB0_1184
	s_and_b32 s0, s83, 0x3c0
	v_or_b32_e32 v76, s0, v83
	s_and_b32 s0, s85, 0x7fffffc0
	v_add_u32_e32 v66, s0, v85
	v_lshlrev_b32_e32 v0, 2, v76
	v_lshl_add_u64 v[62:63], s[18:19], 0, v[0:1]
	v_or_b32_e32 v0, 1, v66
	v_lshlrev_b64 v[6:7], 12, v[0:1]
	v_or_b32_e32 v0, 2, v66
	v_lshlrev_b64 v[10:11], 12, v[0:1]
	v_or_b32_e32 v0, 3, v66
	v_lshlrev_b64 v[14:15], 12, v[0:1]
	v_or_b32_e32 v0, 4, v66
	v_lshlrev_b64 v[18:19], 12, v[0:1]
	v_or_b32_e32 v0, 5, v66
	v_lshlrev_b64 v[22:23], 12, v[0:1]
	v_or_b32_e32 v0, 6, v66
	v_lshlrev_b64 v[26:27], 12, v[0:1]
	v_or_b32_e32 v0, 7, v66
	v_lshlrev_b64 v[30:31], 12, v[0:1]
	v_or_b32_e32 v0, 8, v66
	v_lshlrev_b64 v[34:35], 12, v[0:1]
	v_or_b32_e32 v0, 9, v66
	v_lshlrev_b64 v[38:39], 12, v[0:1]
	v_or_b32_e32 v0, 10, v66
	v_lshlrev_b64 v[42:43], 12, v[0:1]
	v_or_b32_e32 v0, 11, v66
	v_lshlrev_b64 v[46:47], 12, v[0:1]
	v_or_b32_e32 v0, 12, v66
	v_lshlrev_b64 v[50:51], 12, v[0:1]
	v_or_b32_e32 v0, 13, v66
	v_mov_b32_e32 v67, v1
	v_lshlrev_b64 v[54:55], 12, v[0:1]
	v_or_b32_e32 v0, 14, v66
	v_lshlrev_b64 v[2:3], 12, v[66:67]
	v_lshlrev_b64 v[58:59], 12, v[0:1]
	v_or_b32_e32 v0, 15, v66
	v_lshl_add_u64 v[2:3], v[62:63], 0, v[2:3]
	v_lshl_add_u64 v[6:7], v[62:63], 0, v[6:7]
	v_lshl_add_u64 v[10:11], v[62:63], 0, v[10:11]
	v_lshl_add_u64 v[14:15], v[62:63], 0, v[14:15]
	v_lshl_add_u64 v[18:19], v[62:63], 0, v[18:19]
	v_lshl_add_u64 v[22:23], v[62:63], 0, v[22:23]
	v_lshl_add_u64 v[26:27], v[62:63], 0, v[26:27]
	v_lshl_add_u64 v[30:31], v[62:63], 0, v[30:31]
	v_lshlrev_b64 v[64:65], 12, v[0:1]
	global_load_dwordx4 v[2:5], v[2:3], off
	v_lshl_add_u64 v[34:35], v[62:63], 0, v[34:35]
	global_load_dwordx4 v[6:9], v[6:7], off
	v_lshl_add_u64 v[38:39], v[62:63], 0, v[38:39]
	global_load_dwordx4 v[10:13], v[10:11], off
	v_lshl_add_u64 v[42:43], v[62:63], 0, v[42:43]
	global_load_dwordx4 v[14:17], v[14:15], off
	v_lshl_add_u64 v[46:47], v[62:63], 0, v[46:47]
	global_load_dwordx4 v[18:21], v[18:19], off
	v_lshl_add_u64 v[50:51], v[62:63], 0, v[50:51]
	global_load_dwordx4 v[22:25], v[22:23], off
	v_lshl_add_u64 v[54:55], v[62:63], 0, v[54:55]
	global_load_dwordx4 v[26:29], v[26:27], off
	v_lshl_add_u64 v[58:59], v[62:63], 0, v[58:59]
	global_load_dwordx4 v[30:33], v[30:31], off
	v_lshl_add_u64 v[62:63], v[62:63], 0, v[64:65]
	global_load_dwordx4 v[34:37], v[34:35], off
	v_lshl_add_u64 v[74:75], v[66:67], 1, s[14:15]
	global_load_dwordx4 v[38:41], v[38:39], off
	v_lshlrev_b32_e32 v0, 11, v76
	global_load_dwordx4 v[42:45], v[42:43], off
	v_lshl_add_u64 v[74:75], v[74:75], 0, v[0:1]
	global_load_dwordx4 v[46:49], v[46:47], off
	s_mov_b64 s[24:25], 0
	global_load_dwordx4 v[50:53], v[50:51], off
	s_waitcnt vmcnt(0)
	v_cvt_pk_bf16_f32 v66, v2, v6
	global_load_dwordx4 v[54:57], v[54:55], off
	v_cvt_pk_bf16_f32 v2, v5, v9
	global_load_dwordx4 v[58:61], v[58:59], off
	v_cvt_pk_bf16_f32 v67, v10, v14
	global_load_dwordx4 v[62:65], v[62:63], off
	v_add_co_u32_e32 v10, vcc, s72, v74
	v_cvt_pk_bf16_f32 v68, v18, v22
	v_cvt_pk_bf16_f32 v69, v26, v30
	v_cvt_pk_bf16_f32 v5, v29, v33
	v_cvt_pk_bf16_f32 v70, v34, v38
	v_cvt_pk_bf16_f32 v6, v37, v41
	v_cvt_pk_bf16_f32 v71, v42, v46
	s_waitcnt vmcnt(0)
	v_cvt_pk_bf16_f32 v72, v50, v54
	v_cvt_pk_bf16_f32 v73, v58, v62
	global_store_dwordx4 v[74:75], v[66:69], off sc0 sc1
	global_store_dwordx4 v[74:75], v[70:73], off offset:16 sc0 sc1
	v_cvt_pk_bf16_f32 v9, v61, v65
	v_cvt_pk_bf16_f32 v66, v3, v7
	v_cvt_pk_bf16_f32 v67, v11, v15
	v_cvt_pk_bf16_f32 v68, v19, v23
	v_cvt_pk_bf16_f32 v69, v27, v31
	v_cvt_pk_bf16_f32 v70, v35, v39
	v_cvt_pk_bf16_f32 v71, v43, v47
	v_cvt_pk_bf16_f32 v72, v51, v55
	v_cvt_pk_bf16_f32 v73, v59, v63
	global_store_dwordx4 v[74:75], v[66:69], off offset:2048 sc0 sc1
	global_store_dwordx4 v[74:75], v[70:73], off offset:2064 sc0 sc1
	v_addc_co_u32_e32 v11, vcc, 0, v75, vcc
	v_cvt_pk_bf16_f32 v66, v4, v8
	v_cvt_pk_bf16_f32 v67, v12, v16
	v_cvt_pk_bf16_f32 v68, v20, v24
	v_cvt_pk_bf16_f32 v69, v28, v32
	v_cvt_pk_bf16_f32 v3, v13, v17
	v_cvt_pk_bf16_f32 v4, v21, v25
	v_cvt_pk_bf16_f32 v70, v36, v40
	v_cvt_pk_bf16_f32 v71, v44, v48
	v_cvt_pk_bf16_f32 v72, v52, v56
	v_cvt_pk_bf16_f32 v73, v60, v64
	global_store_dwordx4 v[10:11], v[66:69], off sc0 sc1
	global_store_dwordx4 v[10:11], v[70:73], off offset:16 sc0 sc1
	v_cvt_pk_bf16_f32 v7, v45, v49
	v_cvt_pk_bf16_f32 v8, v53, v57
	global_store_dwordx4 v[10:11], v[2:5], off offset:2048 sc0 sc1
	global_store_dwordx4 v[10:11], v[6:9], off offset:2064 sc0 sc1

.LBB0_1189:
	v_ashrrev_i32_e32 v55, 31, v54
	v_lshl_add_u64 v[48:49], v[56:57], 1, s[20:21]
	v_lshlrev_b64 v[28:29], 11, v[54:55]
	v_cvt_pk_bf16_f32 v44, v68, v66
	v_cvt_pk_bf16_f32 v45, v64, v80
	v_cvt_pk_bf16_f32 v46, v74, v76
	v_cvt_pk_bf16_f32 v47, v78, v50
	v_cvt_pk_bf16_f32 v91, v6, v2
	v_lshl_add_u64 v[28:29], v[48:49], 0, v[28:29]
	v_add_u32_e32 v2, 1, v54
	v_cvt_pk_bf16_f32 v88, v38, v42
	v_cvt_pk_bf16_f32 v89, v34, v26
	v_cvt_pk_bf16_f32 v90, v18, v10
	global_store_dwordx4 v[28:29], v[44:47], off sc0 sc1
	global_store_dwordx4 v[28:29], v[88:91], off offset:16 sc0 sc1
	v_cvt_pk_bf16_f32 v29, v7, v3
	v_ashrrev_i32_e32 v3, 31, v2
	v_lshlrev_b64 v[2:3], 11, v[2:3]
	v_cvt_pk_bf16_f32 v44, v69, v67
	v_cvt_pk_bf16_f32 v45, v65, v81
	v_cvt_pk_bf16_f32 v46, v75, v77
	v_cvt_pk_bf16_f32 v47, v79, v51
	v_lshl_add_u64 v[2:3], v[48:49], 0, v[2:3]
	v_cvt_pk_bf16_f32 v26, v39, v43
	v_cvt_pk_bf16_f32 v27, v35, v27
	v_cvt_pk_bf16_f32 v28, v19, v11
	global_store_dwordx4 v[2:3], v[44:47], off sc0 sc1
	global_store_dwordx4 v[2:3], v[26:29], off offset:16 sc0 sc1
	v_add_u32_e32 v2, 2, v54
	v_ashrrev_i32_e32 v3, 31, v2
	v_add_u32_e32 v6, 3, v54
	v_lshlrev_b64 v[2:3], 11, v[2:3]
	v_ashrrev_i32_e32 v7, 31, v6
	v_cvt_pk_bf16_f32 v26, v62, v60
	v_cvt_pk_bf16_f32 v27, v58, v72
	v_cvt_pk_bf16_f32 v28, v70, v40
	v_cvt_pk_bf16_f32 v29, v32, v30
	v_lshl_add_u64 v[2:3], v[48:49], 0, v[2:3]
	v_lshlrev_b64 v[6:7], 11, v[6:7]
	v_cvt_pk_bf16_f32 v34, v14, v16
	v_cvt_pk_bf16_f32 v35, v22, v24
	v_cvt_pk_bf16_f32 v36, v20, v12
	v_cvt_pk_bf16_f32 v37, v8, v4
	global_store_dwordx4 v[2:3], v[26:29], off sc0 sc1
	global_store_dwordx4 v[2:3], v[34:37], off offset:16 sc0 sc1
	v_lshl_add_u64 v[6:7], v[48:49], 0, v[6:7]
	v_cvt_pk_bf16_f32 v26, v63, v61
	v_cvt_pk_bf16_f32 v27, v59, v73
	v_cvt_pk_bf16_f32 v28, v71, v41
	v_cvt_pk_bf16_f32 v29, v33, v31
	v_cvt_pk_bf16_f32 v2, v15, v17
	v_cvt_pk_bf16_f32 v3, v23, v25
	v_cvt_pk_bf16_f32 v4, v21, v13
	v_cvt_pk_bf16_f32 v5, v9, v5
	global_store_dwordx4 v[6:7], v[26:29], off sc0 sc1
	global_store_dwordx4 v[6:7], v[2:5], off offset:16 sc0 sc1

.LBB0_1191:
	s_andn2_b64 vcc, exec, s[24:25]
	s_cbranch_vccnz .LBB0_1169
	s_cmpk_gt_i32 s51, 0xbf
	s_mov_b64 s[24:25], -1
	s_cbranch_scc0 .LBB0_1206
	s_cmpk_gt_u32 s51, 0x14f
	s_cbranch_scc0 .LBB0_1201
	s_cmpk_gt_u32 s51, 0x1cf
	s_cbranch_scc0 .LBB0_1196
	s_and_b32 s0, s83, 0x3c0
	v_or_b32_e32 v76, s0, v83
	s_and_b32 s0, s85, 0x7fffffc0
	v_add_u32_e32 v66, s0, v86
	v_lshlrev_b32_e32 v0, 2, v76
	v_lshl_add_u64 v[62:63], s[80:81], 0, v[0:1]
	v_or_b32_e32 v0, 1, v66
	v_lshlrev_b64 v[6:7], 12, v[0:1]
	v_or_b32_e32 v0, 2, v66
	v_lshlrev_b64 v[10:11], 12, v[0:1]
	v_or_b32_e32 v0, 3, v66
	v_lshlrev_b64 v[14:15], 12, v[0:1]
	v_or_b32_e32 v0, 4, v66
	v_lshlrev_b64 v[18:19], 12, v[0:1]
	v_or_b32_e32 v0, 5, v66
	v_lshlrev_b64 v[22:23], 12, v[0:1]
	v_or_b32_e32 v0, 6, v66
	v_lshlrev_b64 v[26:27], 12, v[0:1]
	v_or_b32_e32 v0, 7, v66
	v_lshlrev_b64 v[30:31], 12, v[0:1]
	v_or_b32_e32 v0, 8, v66
	v_lshlrev_b64 v[34:35], 12, v[0:1]
	v_or_b32_e32 v0, 9, v66
	v_lshlrev_b64 v[38:39], 12, v[0:1]
	v_or_b32_e32 v0, 10, v66
	v_lshlrev_b64 v[42:43], 12, v[0:1]
	v_or_b32_e32 v0, 11, v66
	v_lshlrev_b64 v[46:47], 12, v[0:1]
	v_or_b32_e32 v0, 12, v66
	v_lshlrev_b64 v[50:51], 12, v[0:1]
	v_or_b32_e32 v0, 13, v66
	v_mov_b32_e32 v67, v1
	v_lshlrev_b64 v[54:55], 12, v[0:1]
	v_or_b32_e32 v0, 14, v66
	v_lshlrev_b64 v[2:3], 12, v[66:67]
	v_lshlrev_b64 v[58:59], 12, v[0:1]
	v_or_b32_e32 v0, 15, v66
	v_lshl_add_u64 v[2:3], v[62:63], 0, v[2:3]
	v_lshl_add_u64 v[6:7], v[62:63], 0, v[6:7]
	v_lshl_add_u64 v[10:11], v[62:63], 0, v[10:11]
	v_lshl_add_u64 v[14:15], v[62:63], 0, v[14:15]
	v_lshl_add_u64 v[18:19], v[62:63], 0, v[18:19]
	v_lshl_add_u64 v[22:23], v[62:63], 0, v[22:23]
	v_lshl_add_u64 v[26:27], v[62:63], 0, v[26:27]
	v_lshl_add_u64 v[30:31], v[62:63], 0, v[30:31]
	v_lshlrev_b64 v[64:65], 12, v[0:1]
	global_load_dwordx4 v[2:5], v[2:3], off
	v_lshl_add_u64 v[34:35], v[62:63], 0, v[34:35]
	global_load_dwordx4 v[6:9], v[6:7], off
	v_lshl_add_u64 v[38:39], v[62:63], 0, v[38:39]
	global_load_dwordx4 v[10:13], v[10:11], off
	v_lshl_add_u64 v[42:43], v[62:63], 0, v[42:43]
	global_load_dwordx4 v[14:17], v[14:15], off
	v_lshl_add_u64 v[46:47], v[62:63], 0, v[46:47]
	global_load_dwordx4 v[18:21], v[18:19], off
	v_lshl_add_u64 v[50:51], v[62:63], 0, v[50:51]
	global_load_dwordx4 v[22:25], v[22:23], off
	v_lshl_add_u64 v[54:55], v[62:63], 0, v[54:55]
	global_load_dwordx4 v[26:29], v[26:27], off
	v_lshl_add_u64 v[58:59], v[62:63], 0, v[58:59]
	global_load_dwordx4 v[30:33], v[30:31], off
	v_lshl_add_u64 v[62:63], v[62:63], 0, v[64:65]
	global_load_dwordx4 v[34:37], v[34:35], off
	v_lshl_add_u64 v[74:75], v[66:67], 1, s[90:91]
	global_load_dwordx4 v[38:41], v[38:39], off
	v_lshlrev_b32_e32 v0, 11, v76
	global_load_dwordx4 v[42:45], v[42:43], off
	v_lshl_add_u64 v[74:75], v[74:75], 0, v[0:1]
	global_load_dwordx4 v[46:49], v[46:47], off
	s_mov_b64 s[24:25], 0
	global_load_dwordx4 v[50:53], v[50:51], off
	s_waitcnt vmcnt(0)
	v_cvt_pk_bf16_f32 v66, v2, v6
	global_load_dwordx4 v[54:57], v[54:55], off
	v_cvt_pk_bf16_f32 v2, v5, v9
	global_load_dwordx4 v[58:61], v[58:59], off
	v_cvt_pk_bf16_f32 v67, v10, v14
	global_load_dwordx4 v[62:65], v[62:63], off
	v_add_co_u32_e32 v10, vcc, s72, v74
	v_cvt_pk_bf16_f32 v68, v18, v22
	v_cvt_pk_bf16_f32 v69, v26, v30
	v_cvt_pk_bf16_f32 v5, v29, v33
	v_cvt_pk_bf16_f32 v70, v34, v38
	v_cvt_pk_bf16_f32 v6, v37, v41
	v_cvt_pk_bf16_f32 v71, v42, v46
	s_waitcnt vmcnt(0)
	v_cvt_pk_bf16_f32 v72, v50, v54
	v_cvt_pk_bf16_f32 v73, v58, v62
	global_store_dwordx4 v[74:75], v[66:69], off sc0 sc1
	global_store_dwordx4 v[74:75], v[70:73], off offset:16 sc0 sc1
	v_cvt_pk_bf16_f32 v9, v61, v65
	v_cvt_pk_bf16_f32 v66, v3, v7
	v_cvt_pk_bf16_f32 v67, v11, v15
	v_cvt_pk_bf16_f32 v68, v19, v23
	v_cvt_pk_bf16_f32 v69, v27, v31
	v_cvt_pk_bf16_f32 v70, v35, v39
	v_cvt_pk_bf16_f32 v71, v43, v47
	v_cvt_pk_bf16_f32 v72, v51, v55
	v_cvt_pk_bf16_f32 v73, v59, v63
	global_store_dwordx4 v[74:75], v[66:69], off offset:2048 sc0 sc1
	global_store_dwordx4 v[74:75], v[70:73], off offset:2064 sc0 sc1
	v_addc_co_u32_e32 v11, vcc, 0, v75, vcc
	v_cvt_pk_bf16_f32 v66, v4, v8
	v_cvt_pk_bf16_f32 v67, v12, v16
	v_cvt_pk_bf16_f32 v68, v20, v24
	v_cvt_pk_bf16_f32 v69, v28, v32
	v_cvt_pk_bf16_f32 v3, v13, v17
	v_cvt_pk_bf16_f32 v4, v21, v25
	v_cvt_pk_bf16_f32 v70, v36, v40
	v_cvt_pk_bf16_f32 v71, v44, v48
	v_cvt_pk_bf16_f32 v72, v52, v56
	v_cvt_pk_bf16_f32 v73, v60, v64
	global_store_dwordx4 v[10:11], v[66:69], off sc0 sc1
	global_store_dwordx4 v[10:11], v[70:73], off offset:16 sc0 sc1
	v_cvt_pk_bf16_f32 v7, v45, v49
	v_cvt_pk_bf16_f32 v8, v53, v57
	global_store_dwordx4 v[10:11], v[2:5], off offset:2048 sc0 sc1
	global_store_dwordx4 v[10:11], v[6:9], off offset:2064 sc0 sc1

.LBB0_1199:
	v_readlane_b32 s22, v248, 32
	v_lshlrev_b32_e32 v0, 1, v0
	v_readlane_b32 s23, v248, 33
	s_waitcnt vmcnt(0)
	v_cvt_pk_bf16_f32 v68, v2, v6
	v_cvt_pk_bf16_f32 v69, v10, v14
	v_lshl_add_u64 v[76:77], s[22:23], 0, v[0:1]
	v_lshlrev_b32_e32 v0, 9, v66
	v_cvt_pk_bf16_f32 v70, v18, v22
	v_cvt_pk_bf16_f32 v71, v26, v30
	v_lshl_add_u64 v[76:77], v[76:77], 0, v[0:1]
	v_cvt_pk_bf16_f32 v72, v34, v38
	v_cvt_pk_bf16_f32 v73, v42, v46
	v_cvt_pk_bf16_f32 v74, v50, v54
	v_cvt_pk_bf16_f32 v75, v58, v62
	global_store_dwordx4 v[76:77], v[68:71], off sc0 sc1
	global_store_dwordx4 v[76:77], v[72:75], off offset:16 sc0 sc1
	v_cvt_pk_bf16_f32 v66, v3, v7
	v_cvt_pk_bf16_f32 v67, v11, v15
	v_cvt_pk_bf16_f32 v68, v19, v23
	v_cvt_pk_bf16_f32 v69, v27, v31
	v_cvt_pk_bf16_f32 v70, v35, v39
	v_cvt_pk_bf16_f32 v71, v43, v47
	v_cvt_pk_bf16_f32 v72, v51, v55
	v_cvt_pk_bf16_f32 v73, v59, v63
	global_store_dwordx4 v[76:77], v[66:69], off offset:512 sc0 sc1
	global_store_dwordx4 v[76:77], v[70:73], off offset:528 sc0 sc1
	v_cvt_pk_bf16_f32 v2, v5, v9
	v_cvt_pk_bf16_f32 v66, v4, v8
	v_cvt_pk_bf16_f32 v67, v12, v16
	v_cvt_pk_bf16_f32 v68, v20, v24
	v_cvt_pk_bf16_f32 v69, v28, v32
	v_cvt_pk_bf16_f32 v3, v13, v17
	v_cvt_pk_bf16_f32 v4, v21, v25
	v_cvt_pk_bf16_f32 v5, v29, v33
	v_cvt_pk_bf16_f32 v70, v36, v40
	v_cvt_pk_bf16_f32 v71, v44, v48
	v_cvt_pk_bf16_f32 v72, v52, v56
	v_cvt_pk_bf16_f32 v73, v60, v64
	global_store_dwordx4 v[76:77], v[66:69], off offset:1024 sc0 sc1
	global_store_dwordx4 v[76:77], v[70:73], off offset:1040 sc0 sc1
	v_cvt_pk_bf16_f32 v6, v37, v41
	v_cvt_pk_bf16_f32 v7, v45, v49
	v_cvt_pk_bf16_f32 v8, v53, v57
	v_cvt_pk_bf16_f32 v9, v61, v65
	global_store_dwordx4 v[76:77], v[2:5], off offset:1536 sc0 sc1
	global_store_dwordx4 v[76:77], v[6:9], off offset:1552 sc0 sc1

.LBB0_1204:
	v_lshlrev_b32_e32 v0, 1, v67
	v_lshl_add_u64 v[76:77], s[30:31], 0, v[0:1]
	v_mul_u32_u24_e32 v0, 0x180, v66
	v_lshlrev_b32_e32 v0, 1, v0
	s_waitcnt vmcnt(0)
	v_cvt_pk_bf16_f32 v68, v2, v6
	v_cvt_pk_bf16_f32 v69, v10, v14
	v_cvt_pk_bf16_f32 v70, v18, v22
	v_cvt_pk_bf16_f32 v71, v26, v30
	v_lshl_add_u64 v[76:77], v[76:77], 0, v[0:1]
	v_cvt_pk_bf16_f32 v72, v34, v38
	v_cvt_pk_bf16_f32 v73, v42, v46
	v_cvt_pk_bf16_f32 v74, v50, v54
	v_cvt_pk_bf16_f32 v75, v58, v62
	global_store_dwordx4 v[76:77], v[68:71], off sc0 sc1
	global_store_dwordx4 v[76:77], v[72:75], off offset:16 sc0 sc1
	v_cvt_pk_bf16_f32 v66, v3, v7
	v_cvt_pk_bf16_f32 v67, v11, v15
	v_cvt_pk_bf16_f32 v68, v19, v23
	v_cvt_pk_bf16_f32 v69, v27, v31
	v_cvt_pk_bf16_f32 v70, v35, v39
	v_cvt_pk_bf16_f32 v71, v43, v47
	v_cvt_pk_bf16_f32 v72, v51, v55
	v_cvt_pk_bf16_f32 v73, v59, v63
	global_store_dwordx4 v[76:77], v[66:69], off offset:768 sc0 sc1
	global_store_dwordx4 v[76:77], v[70:73], off offset:784 sc0 sc1
	v_cvt_pk_bf16_f32 v2, v5, v9
	v_cvt_pk_bf16_f32 v66, v4, v8
	v_cvt_pk_bf16_f32 v67, v12, v16
	v_cvt_pk_bf16_f32 v68, v20, v24
	v_cvt_pk_bf16_f32 v69, v28, v32
	v_cvt_pk_bf16_f32 v3, v13, v17
	v_cvt_pk_bf16_f32 v4, v21, v25
	v_cvt_pk_bf16_f32 v5, v29, v33
	v_cvt_pk_bf16_f32 v70, v36, v40
	v_cvt_pk_bf16_f32 v71, v44, v48
	v_cvt_pk_bf16_f32 v72, v52, v56
	v_cvt_pk_bf16_f32 v73, v60, v64
	global_store_dwordx4 v[76:77], v[66:69], off offset:1536 sc0 sc1
	global_store_dwordx4 v[76:77], v[70:73], off offset:1552 sc0 sc1
	v_cvt_pk_bf16_f32 v6, v37, v41
	v_cvt_pk_bf16_f32 v7, v45, v49
	v_cvt_pk_bf16_f32 v8, v53, v57
	v_cvt_pk_bf16_f32 v9, v61, v65
	global_store_dwordx4 v[76:77], v[2:5], off offset:2304 sc0 sc1
	global_store_dwordx4 v[76:77], v[6:9], off offset:2320 sc0 sc1

.LBB0_1365:
	s_mov_b64 s[6:7], exec
	v_readlane_b32 s0, v251, 23
	s_nop 3
	s_cmp_eq_u32 s0, 0
	s_cbranch_scc1 .Lpd_wb
	v_readlane_b32 s0, v248, 31
	s_nop 3
	s_cmp_lt_u32 s0, 3
	s_cbranch_scc1 .Lpd_nowb
.Lpd_wb:
	buffer_wbl2 sc1
